# GEMM K-loops: barrier closing each compute segment issued 4 MFMAs early with s_setprio 3 over the tail (plus attention DMA address diet)
# speedup vs baseline: 1.0097x; 1.0035x over previous
.LBB0_115:
	ds_read_b128 v[148:151], v154
	ds_read_b128 v[158:161], v154 offset:1024
	ds_read_b128 v[162:165], v154 offset:2048
	ds_read_b128 v[166:169], v154 offset:3072
	ds_read_b128 v[170:173], v155
	ds_read_b128 v[174:177], v155 offset:1024
	ds_read_b128 v[178:181], v155 offset:2048
	ds_read_b128 v[182:185], v155 offset:3072
	s_add_u32 s46, s44, 0xfff00080
	s_addc_u32 s47, s45, -1
	s_cmp_eq_u32 s69, 60
	s_cselect_b32 s49, s35, s47
	s_cselect_b32 s48, s43, s46
	s_cselect_b32 s47, s37, s68
	s_cselect_b32 s46, s66, s67
	v_lshl_add_u64 v[218:219], s[44:45], 0, v[140:141]
	s_add_i32 m0, s54, 0xc000
	ds_read_b128 v[186:189], v156
	ds_read_b128 v[190:193], v156 offset:1024
	ds_read_b128 v[194:197], v156 offset:2048
	ds_read_b128 v[198:201], v156 offset:3072
	ds_read_b128 v[202:205], v156 offset:4096
	ds_read_b128 v[206:209], v156 offset:5120
	ds_read_b128 v[210:213], v156 offset:6144
	ds_read_b128 v[214:217], v156 offset:7168
	global_load_lds_dwordx4 v[218:219], off
	v_lshl_add_u64 v[218:219], s[44:45], 0, v[142:143]
	s_add_i32 m0, s54, 0xe000
	s_nop 0
	global_load_lds_dwordx4 v[218:219], off
	s_waitcnt vmcnt(8)
	s_waitcnt lgkmcnt(0)
	s_barrier
	s_setprio 1
	s_waitcnt lgkmcnt(0)
	v_mfma_f32_16x16x32_bf16 v[126:129], v[148:151], v[186:189], v[126:129]
	v_mfma_f32_16x16x32_bf16 v[122:125], v[162:165], v[186:189], v[122:125]
	v_mfma_f32_16x16x32_bf16 v[118:121], v[148:151], v[194:197], v[118:121]
	v_mfma_f32_16x16x32_bf16 v[110:113], v[162:165], v[194:197], v[110:113]
	v_mfma_f32_16x16x32_bf16 v[102:105], v[148:151], v[202:205], v[102:105]
	v_mfma_f32_16x16x32_bf16 v[94:97], v[162:165], v[202:205], v[94:97]
	v_mfma_f32_16x16x32_bf16 v[86:89], v[148:151], v[210:213], v[86:89]
	v_mfma_f32_16x16x32_bf16 v[78:81], v[162:165], v[210:213], v[78:81]
	v_mfma_f32_16x16x32_bf16 v[126:129], v[158:161], v[190:193], v[126:129]
	v_mfma_f32_16x16x32_bf16 v[122:125], v[166:169], v[190:193], v[122:125]
	v_mfma_f32_16x16x32_bf16 v[118:121], v[158:161], v[198:201], v[118:121]
	v_mfma_f32_16x16x32_bf16 v[110:113], v[166:169], v[198:201], v[110:113]
	v_mfma_f32_16x16x32_bf16 v[102:105], v[158:161], v[206:209], v[102:105]
	v_mfma_f32_16x16x32_bf16 v[94:97], v[166:169], v[206:209], v[94:97]
	v_mfma_f32_16x16x32_bf16 v[86:89], v[158:161], v[214:217], v[86:89]
	v_mfma_f32_16x16x32_bf16 v[78:81], v[166:169], v[214:217], v[78:81]
	s_setprio 0
	s_setprio 1
	v_mfma_f32_16x16x32_bf16 v[114:117], v[170:173], v[186:189], v[114:117]
	v_mfma_f32_16x16x32_bf16 v[106:109], v[178:181], v[186:189], v[106:109]
	v_mfma_f32_16x16x32_bf16 v[98:101], v[170:173], v[194:197], v[98:101]
	v_mfma_f32_16x16x32_bf16 v[90:93], v[178:181], v[194:197], v[90:93]
	v_mfma_f32_16x16x32_bf16 v[82:85], v[170:173], v[202:205], v[82:85]
	v_mfma_f32_16x16x32_bf16 v[74:77], v[178:181], v[202:205], v[74:77]
	v_mfma_f32_16x16x32_bf16 v[70:73], v[170:173], v[210:213], v[70:73]
	v_mfma_f32_16x16x32_bf16 v[66:69], v[178:181], v[210:213], v[66:69]
	v_mfma_f32_16x16x32_bf16 v[114:117], v[174:177], v[190:193], v[114:117]
	v_mfma_f32_16x16x32_bf16 v[106:109], v[182:185], v[190:193], v[106:109]
	v_mfma_f32_16x16x32_bf16 v[98:101], v[174:177], v[198:201], v[98:101]
	v_mfma_f32_16x16x32_bf16 v[90:93], v[182:185], v[198:201], v[90:93]
	s_setprio 3
	s_barrier
	v_mfma_f32_16x16x32_bf16 v[82:85], v[174:177], v[206:209], v[82:85]
	v_mfma_f32_16x16x32_bf16 v[74:77], v[182:185], v[206:209], v[74:77]
	v_mfma_f32_16x16x32_bf16 v[70:73], v[174:177], v[214:217], v[70:73]
	v_mfma_f32_16x16x32_bf16 v[66:69], v[182:185], v[214:217], v[66:69]
	s_setprio 0
	s_add_i32 s70, s64, s51
	v_lshl_add_u64 v[218:219], s[46:47], 0, v[134:135]
	s_mov_b32 m0, s70
	ds_read_b128 v[186:189], v156 offset:16384
	ds_read_b128 v[190:193], v156 offset:17408
	ds_read_b128 v[194:197], v156 offset:18432
	ds_read_b128 v[198:201], v156 offset:19456
	ds_read_b128 v[202:205], v156 offset:20480
	ds_read_b128 v[206:209], v156 offset:21504
	ds_read_b128 v[210:213], v156 offset:22528
	ds_read_b128 v[214:217], v156 offset:23552
	global_load_lds_dwordx4 v[218:219], off
	s_add_i32 m0, s70, 0x2000
	s_add_u32 s70, s46, 0x100000
	v_lshl_add_u64 v[220:221], s[46:47], 0, v[130:131]
	s_addc_u32 s71, s47, 0
	s_add_i32 s72, s65, s51
	global_load_lds_dwordx4 v[220:221], off
	v_lshl_add_u64 v[222:223], s[70:71], 0, v[134:135]
	s_mov_b32 m0, s72
	v_lshl_add_u64 v[224:225], s[48:49], 0, v[132:133]
	global_load_lds_dwordx4 v[222:223], off
	v_lshl_add_u64 v[222:223], s[70:71], 0, v[130:131]
	s_add_i32 m0, s72, 0x2000
	s_nop 0
	global_load_lds_dwordx4 v[222:223], off
	v_lshl_add_u64 v[222:223], s[48:49], 0, v[136:137]
	s_mov_b32 m0, s54
	s_nop 0
	global_load_lds_dwordx4 v[222:223], off
	s_mov_b32 m0, s55
	s_nop 0
	global_load_lds_dwordx4 v[224:225], off
	s_waitcnt vmcnt(8)
	s_waitcnt lgkmcnt(0)
	s_barrier
	s_setprio 1
	s_waitcnt lgkmcnt(0)
	v_mfma_f32_16x16x32_bf16 v[62:65], v[148:151], v[186:189], v[62:65]
	v_mfma_f32_16x16x32_bf16 v[58:61], v[162:165], v[186:189], v[58:61]
	v_mfma_f32_16x16x32_bf16 v[54:57], v[148:151], v[194:197], v[54:57]
	v_mfma_f32_16x16x32_bf16 v[46:49], v[162:165], v[194:197], v[46:49]
	v_mfma_f32_16x16x32_bf16 v[38:41], v[148:151], v[202:205], v[38:41]
	v_mfma_f32_16x16x32_bf16 v[30:33], v[162:165], v[202:205], v[30:33]
	v_mfma_f32_16x16x32_bf16 v[22:25], v[148:151], v[210:213], v[22:25]
	v_mfma_f32_16x16x32_bf16 v[14:17], v[162:165], v[210:213], v[14:17]
	v_mfma_f32_16x16x32_bf16 v[62:65], v[158:161], v[190:193], v[62:65]
	v_mfma_f32_16x16x32_bf16 v[58:61], v[166:169], v[190:193], v[58:61]
	v_mfma_f32_16x16x32_bf16 v[54:57], v[158:161], v[198:201], v[54:57]
	v_mfma_f32_16x16x32_bf16 v[46:49], v[166:169], v[198:201], v[46:49]
	v_mfma_f32_16x16x32_bf16 v[38:41], v[158:161], v[206:209], v[38:41]
	v_mfma_f32_16x16x32_bf16 v[30:33], v[166:169], v[206:209], v[30:33]
	v_mfma_f32_16x16x32_bf16 v[22:25], v[158:161], v[214:217], v[22:25]
	v_mfma_f32_16x16x32_bf16 v[14:17], v[166:169], v[214:217], v[14:17]
	s_setprio 0
	s_setprio 1
	v_mfma_f32_16x16x32_bf16 v[50:53], v[170:173], v[186:189], v[50:53]
	v_mfma_f32_16x16x32_bf16 v[42:45], v[178:181], v[186:189], v[42:45]
	v_mfma_f32_16x16x32_bf16 v[34:37], v[170:173], v[194:197], v[34:37]
	v_mfma_f32_16x16x32_bf16 v[26:29], v[178:181], v[194:197], v[26:29]
	v_mfma_f32_16x16x32_bf16 v[18:21], v[170:173], v[202:205], v[18:21]
	v_mfma_f32_16x16x32_bf16 v[10:13], v[178:181], v[202:205], v[10:13]
	v_mfma_f32_16x16x32_bf16 v[6:9], v[170:173], v[210:213], v[6:9]
	v_mfma_f32_16x16x32_bf16 v[2:5], v[178:181], v[210:213], v[2:5]
	v_mfma_f32_16x16x32_bf16 v[50:53], v[174:177], v[190:193], v[50:53]
	v_mfma_f32_16x16x32_bf16 v[42:45], v[182:185], v[190:193], v[42:45]
	v_mfma_f32_16x16x32_bf16 v[34:37], v[174:177], v[198:201], v[34:37]
	v_mfma_f32_16x16x32_bf16 v[26:29], v[182:185], v[198:201], v[26:29]
	s_setprio 3
	s_barrier
	v_mfma_f32_16x16x32_bf16 v[18:21], v[174:177], v[206:209], v[18:21]
	v_mfma_f32_16x16x32_bf16 v[10:13], v[182:185], v[206:209], v[10:13]
	v_mfma_f32_16x16x32_bf16 v[6:9], v[174:177], v[214:217], v[6:9]
	v_mfma_f32_16x16x32_bf16 v[2:5], v[182:185], v[214:217], v[2:5]
	s_setprio 0
	s_add_i32 s70, 0, 0x18000
	v_add_u32_e32 v138, s70, v152
	s_add_i32 s71, 0, 0x1c000
	ds_read_b128 v[148:151], v138
	ds_read_b128 v[158:161], v138 offset:1024
	ds_read_b128 v[162:165], v138 offset:2048
	ds_read_b128 v[166:169], v138 offset:3072
	v_add_u32_e32 v138, s71, v152
	ds_read_b128 v[170:173], v138
	ds_read_b128 v[174:177], v138 offset:1024
	ds_read_b128 v[178:181], v138 offset:2048
	ds_read_b128 v[182:185], v138 offset:3072
	s_add_u32 s48, s48, 0x100000
	s_addc_u32 s49, s49, 0
	s_mov_b32 m0, s56
	v_lshl_add_u64 v[226:227], s[48:49], 0, v[136:137]
	ds_read_b128 v[186:189], v156 offset:32768
	ds_read_b128 v[190:193], v156 offset:33792
	ds_read_b128 v[194:197], v156 offset:34816
	ds_read_b128 v[198:201], v156 offset:35840
	ds_read_b128 v[202:205], v156 offset:36864
	ds_read_b128 v[206:209], v156 offset:37888
	ds_read_b128 v[210:213], v156 offset:38912
	ds_read_b128 v[214:217], v156 offset:39936
	global_load_lds_dwordx4 v[226:227], off
	v_lshl_add_u64 v[226:227], s[48:49], 0, v[132:133]
	s_mov_b32 m0, s57
	s_nop 0
	global_load_lds_dwordx4 v[226:227], off
	s_waitcnt vmcnt(8)
	s_waitcnt lgkmcnt(0)
	s_barrier
	s_setprio 1
	s_waitcnt lgkmcnt(0)
	v_mfma_f32_16x16x32_bf16 v[126:129], v[148:151], v[186:189], v[126:129]
	v_mfma_f32_16x16x32_bf16 v[122:125], v[162:165], v[186:189], v[122:125]
	v_mfma_f32_16x16x32_bf16 v[118:121], v[148:151], v[194:197], v[118:121]
	v_mfma_f32_16x16x32_bf16 v[110:113], v[162:165], v[194:197], v[110:113]
	v_mfma_f32_16x16x32_bf16 v[102:105], v[148:151], v[202:205], v[102:105]
	v_mfma_f32_16x16x32_bf16 v[94:97], v[162:165], v[202:205], v[94:97]
	v_mfma_f32_16x16x32_bf16 v[86:89], v[148:151], v[210:213], v[86:89]
	v_mfma_f32_16x16x32_bf16 v[78:81], v[162:165], v[210:213], v[78:81]
	v_mfma_f32_16x16x32_bf16 v[126:129], v[158:161], v[190:193], v[126:129]
	v_mfma_f32_16x16x32_bf16 v[122:125], v[166:169], v[190:193], v[122:125]
	v_mfma_f32_16x16x32_bf16 v[118:121], v[158:161], v[198:201], v[118:121]
	v_mfma_f32_16x16x32_bf16 v[110:113], v[166:169], v[198:201], v[110:113]
	v_mfma_f32_16x16x32_bf16 v[102:105], v[158:161], v[206:209], v[102:105]
	v_mfma_f32_16x16x32_bf16 v[94:97], v[166:169], v[206:209], v[94:97]
	v_mfma_f32_16x16x32_bf16 v[86:89], v[158:161], v[214:217], v[86:89]
	v_mfma_f32_16x16x32_bf16 v[78:81], v[166:169], v[214:217], v[78:81]
	s_setprio 0
	s_setprio 1
	v_mfma_f32_16x16x32_bf16 v[114:117], v[170:173], v[186:189], v[114:117]
	v_mfma_f32_16x16x32_bf16 v[106:109], v[178:181], v[186:189], v[106:109]
	v_mfma_f32_16x16x32_bf16 v[98:101], v[170:173], v[194:197], v[98:101]
	v_mfma_f32_16x16x32_bf16 v[90:93], v[178:181], v[194:197], v[90:93]
	v_mfma_f32_16x16x32_bf16 v[82:85], v[170:173], v[202:205], v[82:85]
	v_mfma_f32_16x16x32_bf16 v[74:77], v[178:181], v[202:205], v[74:77]
	v_mfma_f32_16x16x32_bf16 v[70:73], v[170:173], v[210:213], v[70:73]
	v_mfma_f32_16x16x32_bf16 v[66:69], v[178:181], v[210:213], v[66:69]
	v_mfma_f32_16x16x32_bf16 v[114:117], v[174:177], v[190:193], v[114:117]
	v_mfma_f32_16x16x32_bf16 v[106:109], v[182:185], v[190:193], v[106:109]
	v_mfma_f32_16x16x32_bf16 v[98:101], v[174:177], v[198:201], v[98:101]
	v_mfma_f32_16x16x32_bf16 v[90:93], v[182:185], v[198:201], v[90:93]
	s_setprio 3
	s_barrier
	v_mfma_f32_16x16x32_bf16 v[82:85], v[174:177], v[206:209], v[82:85]
	v_mfma_f32_16x16x32_bf16 v[74:77], v[182:185], v[206:209], v[74:77]
	v_mfma_f32_16x16x32_bf16 v[70:73], v[174:177], v[214:217], v[70:73]
	v_mfma_f32_16x16x32_bf16 v[66:69], v[182:185], v[214:217], v[66:69]
	s_setprio 0
	s_add_i32 s48, s70, s51
	v_lshl_add_u64 v[218:219], v[218:219], 0, s[28:29]
	s_mov_b32 m0, s48
	ds_read_b128 v[186:189], v156 offset:49152
	ds_read_b128 v[190:193], v156 offset:50176
	ds_read_b128 v[194:197], v156 offset:51200
	ds_read_b128 v[198:201], v156 offset:52224
	ds_read_b128 v[202:205], v156 offset:53248
	ds_read_b128 v[206:209], v156 offset:54272
	ds_read_b128 v[210:213], v156 offset:55296
	ds_read_b128 v[214:217], v156 offset:56320
	global_load_lds_dwordx4 v[218:219], off
	s_add_i32 m0, s48, 0x2000
	s_add_u32 s46, s46, 0x100080
	v_lshl_add_u64 v[218:219], v[220:221], 0, s[28:29]
	s_addc_u32 s47, s47, 0
	s_add_i32 s48, s71, s51
	global_load_lds_dwordx4 v[218:219], off
	v_lshl_add_u64 v[218:219], s[46:47], 0, v[134:135]
	s_mov_b32 m0, s48
	s_nop 0
	global_load_lds_dwordx4 v[218:219], off
	v_lshl_add_u64 v[218:219], s[46:47], 0, v[130:131]
	s_add_i32 m0, s48, 0x2000
	s_nop 0
	global_load_lds_dwordx4 v[218:219], off
	v_lshl_add_u64 v[218:219], v[222:223], 0, s[28:29]
	s_mov_b32 m0, s59
	s_nop 0
	global_load_lds_dwordx4 v[218:219], off
	v_lshl_add_u64 v[218:219], v[224:225], 0, s[28:29]
	s_mov_b32 m0, s60
	s_nop 0
	global_load_lds_dwordx4 v[218:219], off
	s_waitcnt vmcnt(8)
	s_waitcnt lgkmcnt(0)
	s_barrier
	s_setprio 1
	s_waitcnt lgkmcnt(0)
	v_mfma_f32_16x16x32_bf16 v[62:65], v[148:151], v[186:189], v[62:65]
	v_mfma_f32_16x16x32_bf16 v[58:61], v[162:165], v[186:189], v[58:61]
	v_mfma_f32_16x16x32_bf16 v[54:57], v[148:151], v[194:197], v[54:57]
	v_mfma_f32_16x16x32_bf16 v[46:49], v[162:165], v[194:197], v[46:49]
	v_mfma_f32_16x16x32_bf16 v[38:41], v[148:151], v[202:205], v[38:41]
	v_mfma_f32_16x16x32_bf16 v[30:33], v[162:165], v[202:205], v[30:33]
	v_mfma_f32_16x16x32_bf16 v[22:25], v[148:151], v[210:213], v[22:25]
	v_mfma_f32_16x16x32_bf16 v[14:17], v[162:165], v[210:213], v[14:17]
	v_mfma_f32_16x16x32_bf16 v[62:65], v[158:161], v[190:193], v[62:65]
	v_mfma_f32_16x16x32_bf16 v[58:61], v[166:169], v[190:193], v[58:61]
	v_mfma_f32_16x16x32_bf16 v[54:57], v[158:161], v[198:201], v[54:57]
	v_mfma_f32_16x16x32_bf16 v[46:49], v[166:169], v[198:201], v[46:49]
	v_mfma_f32_16x16x32_bf16 v[38:41], v[158:161], v[206:209], v[38:41]
	v_mfma_f32_16x16x32_bf16 v[30:33], v[166:169], v[206:209], v[30:33]
	v_mfma_f32_16x16x32_bf16 v[22:25], v[158:161], v[214:217], v[22:25]
	v_mfma_f32_16x16x32_bf16 v[14:17], v[166:169], v[214:217], v[14:17]
	s_setprio 0
	s_setprio 1
	v_mfma_f32_16x16x32_bf16 v[50:53], v[170:173], v[186:189], v[50:53]
	v_mfma_f32_16x16x32_bf16 v[42:45], v[178:181], v[186:189], v[42:45]
	v_mfma_f32_16x16x32_bf16 v[34:37], v[170:173], v[194:197], v[34:37]
	v_mfma_f32_16x16x32_bf16 v[26:29], v[178:181], v[194:197], v[26:29]
	v_mfma_f32_16x16x32_bf16 v[18:21], v[170:173], v[202:205], v[18:21]
	v_mfma_f32_16x16x32_bf16 v[10:13], v[178:181], v[202:205], v[10:13]
	v_mfma_f32_16x16x32_bf16 v[6:9], v[170:173], v[210:213], v[6:9]
	v_mfma_f32_16x16x32_bf16 v[2:5], v[178:181], v[210:213], v[2:5]
	v_mfma_f32_16x16x32_bf16 v[50:53], v[174:177], v[190:193], v[50:53]
	v_mfma_f32_16x16x32_bf16 v[42:45], v[182:185], v[190:193], v[42:45]
	v_mfma_f32_16x16x32_bf16 v[34:37], v[174:177], v[198:201], v[34:37]
	v_mfma_f32_16x16x32_bf16 v[26:29], v[182:185], v[198:201], v[26:29]
	s_setprio 3
	s_barrier
	v_mfma_f32_16x16x32_bf16 v[18:21], v[174:177], v[206:209], v[18:21]
	v_mfma_f32_16x16x32_bf16 v[10:13], v[182:185], v[206:209], v[10:13]
	v_mfma_f32_16x16x32_bf16 v[6:9], v[174:177], v[214:217], v[6:9]
	v_mfma_f32_16x16x32_bf16 v[2:5], v[182:185], v[214:217], v[2:5]
	s_setprio 0
	s_add_i32 s69, s69, 2
	s_add_u32 s44, s44, 0x100
	s_addc_u32 s45, s45, 0
	s_add_u32 s67, s67, 0x100
	s_addc_u32 s68, s68, 0
	s_cmp_gt_u32 s69, 61
	s_cbranch_scc0 .LBB0_115
	s_and_b64 vcc, exec, s[30:31]
	s_cbranch_vccz .LBB0_118
	s_barrier

.LBB0_540:
	v_add_u32_e32 v139, s64, v186
	ds_read_b128 v[130:133], v139
	ds_read_b128 v[134:137], v139 offset:1024
	ds_read_b128 v[146:149], v139 offset:2048
	ds_read_b128 v[150:153], v139 offset:3072
	v_add_u32_e32 v139, s65, v186
	s_add_u32 s48, s44, s46
	ds_read_b128 v[154:157], v139
	ds_read_b128 v[174:177], v139 offset:1024
	ds_read_b128 v[178:181], v139 offset:2048
	ds_read_b128 v[182:185], v139 offset:3072
	s_addc_u32 s49, s45, s47
	s_add_u32 s48, s48, 0x100
	s_addc_u32 s49, s49, 0
	s_add_u32 s71, s68, s46
	s_addc_u32 s72, s69, s47
	s_cmpk_eq_i32 s46, 0x1f00
	s_cselect_b32 s51, s39, s49
	s_cselect_b32 s50, s66, s48
	s_cselect_b32 s49, s37, s72
	s_cselect_b32 s48, s67, s71
	v_lshl_add_u64 v[222:223], v[142:143], 0, s[46:47]
	s_add_i32 m0, s55, 0xc000
	ds_read_b128 v[190:193], v188
	ds_read_b128 v[194:197], v188 offset:1024
	ds_read_b128 v[198:201], v188 offset:2048
	ds_read_b128 v[202:205], v188 offset:3072
	ds_read_b128 v[206:209], v188 offset:4096
	ds_read_b128 v[210:213], v188 offset:5120
	ds_read_b128 v[214:217], v188 offset:6144
	ds_read_b128 v[218:221], v188 offset:7168
	global_load_lds_dwordx4 v[222:223], off
	v_lshl_add_u64 v[222:223], v[144:145], 0, s[46:47]
	s_add_i32 m0, s55, 0xe000
	s_nop 0
	global_load_lds_dwordx4 v[222:223], off
	s_waitcnt vmcnt(8)
	s_waitcnt lgkmcnt(0)
	s_barrier
	s_setprio 1
	s_waitcnt lgkmcnt(0)
	v_mfma_f32_16x16x32_bf16 v[126:129], v[130:133], v[190:193], v[126:129]
	v_mfma_f32_16x16x32_bf16 v[122:125], v[146:149], v[190:193], v[122:125]
	v_mfma_f32_16x16x32_bf16 v[114:117], v[130:133], v[198:201], v[114:117]
	v_mfma_f32_16x16x32_bf16 v[106:109], v[146:149], v[198:201], v[106:109]
	v_mfma_f32_16x16x32_bf16 v[98:101], v[130:133], v[206:209], v[98:101]
	v_mfma_f32_16x16x32_bf16 v[90:93], v[146:149], v[206:209], v[90:93]
	v_mfma_f32_16x16x32_bf16 v[82:85], v[130:133], v[214:217], v[82:85]
	v_mfma_f32_16x16x32_bf16 v[74:77], v[146:149], v[214:217], v[74:77]
	v_mfma_f32_16x16x32_bf16 v[126:129], v[134:137], v[194:197], v[126:129]
	v_mfma_f32_16x16x32_bf16 v[122:125], v[150:153], v[194:197], v[122:125]
	v_mfma_f32_16x16x32_bf16 v[114:117], v[134:137], v[202:205], v[114:117]
	v_mfma_f32_16x16x32_bf16 v[106:109], v[150:153], v[202:205], v[106:109]
	v_mfma_f32_16x16x32_bf16 v[98:101], v[134:137], v[210:213], v[98:101]
	v_mfma_f32_16x16x32_bf16 v[90:93], v[150:153], v[210:213], v[90:93]
	v_mfma_f32_16x16x32_bf16 v[82:85], v[134:137], v[218:221], v[82:85]
	v_mfma_f32_16x16x32_bf16 v[74:77], v[150:153], v[218:221], v[74:77]
	s_setprio 0
	s_setprio 1
	v_mfma_f32_16x16x32_bf16 v[118:121], v[154:157], v[190:193], v[118:121]
	v_mfma_f32_16x16x32_bf16 v[110:113], v[178:181], v[190:193], v[110:113]
	v_mfma_f32_16x16x32_bf16 v[102:105], v[154:157], v[198:201], v[102:105]
	v_mfma_f32_16x16x32_bf16 v[94:97], v[178:181], v[198:201], v[94:97]
	v_mfma_f32_16x16x32_bf16 v[86:89], v[154:157], v[206:209], v[86:89]
	v_mfma_f32_16x16x32_bf16 v[78:81], v[178:181], v[206:209], v[78:81]
	v_mfma_f32_16x16x32_bf16 v[70:73], v[154:157], v[214:217], v[70:73]
	v_mfma_f32_16x16x32_bf16 v[66:69], v[178:181], v[214:217], v[66:69]
	v_mfma_f32_16x16x32_bf16 v[118:121], v[174:177], v[194:197], v[118:121]
	v_mfma_f32_16x16x32_bf16 v[110:113], v[182:185], v[194:197], v[110:113]
	v_mfma_f32_16x16x32_bf16 v[102:105], v[174:177], v[202:205], v[102:105]
	v_mfma_f32_16x16x32_bf16 v[94:97], v[182:185], v[202:205], v[94:97]
	s_setprio 3
	s_barrier
	v_mfma_f32_16x16x32_bf16 v[86:89], v[174:177], v[210:213], v[86:89]
	v_mfma_f32_16x16x32_bf16 v[78:81], v[182:185], v[210:213], v[78:81]
	v_mfma_f32_16x16x32_bf16 v[70:73], v[174:177], v[218:221], v[70:73]
	v_mfma_f32_16x16x32_bf16 v[66:69], v[182:185], v[218:221], v[66:69]
	s_setprio 0
	s_add_i32 s71, s64, s54
	v_lshl_add_u64 v[222:223], s[48:49], 0, v[160:161]
	s_mov_b32 m0, s71
	ds_read_b128 v[190:193], v188 offset:16384
	ds_read_b128 v[194:197], v188 offset:17408
	ds_read_b128 v[198:201], v188 offset:18432
	ds_read_b128 v[202:205], v188 offset:19456
	ds_read_b128 v[206:209], v188 offset:20480
	ds_read_b128 v[210:213], v188 offset:21504
	ds_read_b128 v[214:217], v188 offset:22528
	ds_read_b128 v[218:221], v188 offset:23552
	global_load_lds_dwordx4 v[222:223], off
	s_add_i32 m0, s71, 0x2000
	s_add_u32 s72, s48, 0x100000
	v_lshl_add_u64 v[224:225], s[48:49], 0, v[164:165]
	s_addc_u32 s73, s49, 0
	s_add_i32 s71, s65, s54
	global_load_lds_dwordx4 v[224:225], off
	v_lshl_add_u64 v[226:227], s[72:73], 0, v[160:161]
	s_mov_b32 m0, s71
	v_lshl_add_u64 v[228:229], s[50:51], 0, v[162:163]
	global_load_lds_dwordx4 v[226:227], off
	v_lshl_add_u64 v[226:227], s[72:73], 0, v[164:165]
	s_add_i32 m0, s71, 0x2000
	s_nop 0
	global_load_lds_dwordx4 v[226:227], off
	v_lshl_add_u64 v[226:227], s[50:51], 0, v[158:159]
	s_mov_b32 m0, s55
	s_nop 0
	global_load_lds_dwordx4 v[226:227], off
	s_mov_b32 m0, s56
	s_nop 0
	global_load_lds_dwordx4 v[228:229], off
	s_waitcnt vmcnt(8)
	s_waitcnt lgkmcnt(0)
	s_barrier
	s_setprio 1
	s_waitcnt lgkmcnt(0)
	v_mfma_f32_16x16x32_bf16 v[62:65], v[130:133], v[190:193], v[62:65]
	v_mfma_f32_16x16x32_bf16 v[58:61], v[146:149], v[190:193], v[58:61]
	v_mfma_f32_16x16x32_bf16 v[50:53], v[130:133], v[198:201], v[50:53]
	v_mfma_f32_16x16x32_bf16 v[42:45], v[146:149], v[198:201], v[42:45]
	v_mfma_f32_16x16x32_bf16 v[34:37], v[130:133], v[206:209], v[34:37]
	v_mfma_f32_16x16x32_bf16 v[26:29], v[146:149], v[206:209], v[26:29]
	v_mfma_f32_16x16x32_bf16 v[18:21], v[130:133], v[214:217], v[18:21]
	v_mfma_f32_16x16x32_bf16 v[10:13], v[146:149], v[214:217], v[10:13]
	v_mfma_f32_16x16x32_bf16 v[62:65], v[134:137], v[194:197], v[62:65]
	v_mfma_f32_16x16x32_bf16 v[58:61], v[150:153], v[194:197], v[58:61]
	v_mfma_f32_16x16x32_bf16 v[50:53], v[134:137], v[202:205], v[50:53]
	v_mfma_f32_16x16x32_bf16 v[42:45], v[150:153], v[202:205], v[42:45]
	v_mfma_f32_16x16x32_bf16 v[34:37], v[134:137], v[210:213], v[34:37]
	v_mfma_f32_16x16x32_bf16 v[26:29], v[150:153], v[210:213], v[26:29]
	v_mfma_f32_16x16x32_bf16 v[18:21], v[134:137], v[218:221], v[18:21]
	v_mfma_f32_16x16x32_bf16 v[10:13], v[150:153], v[218:221], v[10:13]
	s_setprio 0
	s_setprio 1
	v_mfma_f32_16x16x32_bf16 v[54:57], v[154:157], v[190:193], v[54:57]
	v_mfma_f32_16x16x32_bf16 v[46:49], v[178:181], v[190:193], v[46:49]
	v_mfma_f32_16x16x32_bf16 v[38:41], v[154:157], v[198:201], v[38:41]
	v_mfma_f32_16x16x32_bf16 v[30:33], v[178:181], v[198:201], v[30:33]
	v_mfma_f32_16x16x32_bf16 v[22:25], v[154:157], v[206:209], v[22:25]
	v_mfma_f32_16x16x32_bf16 v[14:17], v[178:181], v[206:209], v[14:17]
	v_mfma_f32_16x16x32_bf16 v[6:9], v[154:157], v[214:217], v[6:9]
	v_mfma_f32_16x16x32_bf16 v[2:5], v[178:181], v[214:217], v[2:5]
	v_mfma_f32_16x16x32_bf16 v[54:57], v[174:177], v[194:197], v[54:57]
	v_mfma_f32_16x16x32_bf16 v[46:49], v[182:185], v[194:197], v[46:49]
	v_mfma_f32_16x16x32_bf16 v[38:41], v[174:177], v[202:205], v[38:41]
	v_mfma_f32_16x16x32_bf16 v[30:33], v[182:185], v[202:205], v[30:33]
	s_setprio 3
	s_barrier
	v_mfma_f32_16x16x32_bf16 v[22:25], v[174:177], v[210:213], v[22:25]
	v_mfma_f32_16x16x32_bf16 v[14:17], v[182:185], v[210:213], v[14:17]
	v_mfma_f32_16x16x32_bf16 v[6:9], v[174:177], v[218:221], v[6:9]
	v_mfma_f32_16x16x32_bf16 v[2:5], v[182:185], v[218:221], v[2:5]
	s_setprio 0
	s_add_i32 s71, 0, 0x18000
	v_add_u32_e32 v139, s71, v186
	s_add_i32 s72, 0, 0x1c000
	ds_read_b128 v[130:133], v139
	ds_read_b128 v[134:137], v139 offset:1024
	ds_read_b128 v[146:149], v139 offset:2048
	ds_read_b128 v[150:153], v139 offset:3072
	v_add_u32_e32 v139, s72, v186
	ds_read_b128 v[154:157], v139
	ds_read_b128 v[174:177], v139 offset:1024
	ds_read_b128 v[178:181], v139 offset:2048
	ds_read_b128 v[182:185], v139 offset:3072
	s_add_u32 s50, s50, 0x100000
	s_addc_u32 s51, s51, 0
	s_mov_b32 m0, s57
	v_lshl_add_u64 v[230:231], s[50:51], 0, v[158:159]
	ds_read_b128 v[190:193], v188 offset:32768
	ds_read_b128 v[194:197], v188 offset:33792
	ds_read_b128 v[198:201], v188 offset:34816
	ds_read_b128 v[202:205], v188 offset:35840
	ds_read_b128 v[206:209], v188 offset:36864
	ds_read_b128 v[210:213], v188 offset:37888
	ds_read_b128 v[214:217], v188 offset:38912
	ds_read_b128 v[218:221], v188 offset:39936
	global_load_lds_dwordx4 v[230:231], off
	v_lshl_add_u64 v[230:231], s[50:51], 0, v[162:163]
	s_mov_b32 m0, s58
	s_nop 0
	global_load_lds_dwordx4 v[230:231], off
	s_waitcnt vmcnt(8)
	s_waitcnt lgkmcnt(0)
	s_barrier
	s_setprio 1
	s_waitcnt lgkmcnt(0)
	v_mfma_f32_16x16x32_bf16 v[126:129], v[130:133], v[190:193], v[126:129]
	v_mfma_f32_16x16x32_bf16 v[122:125], v[146:149], v[190:193], v[122:125]
	v_mfma_f32_16x16x32_bf16 v[114:117], v[130:133], v[198:201], v[114:117]
	v_mfma_f32_16x16x32_bf16 v[106:109], v[146:149], v[198:201], v[106:109]
	v_mfma_f32_16x16x32_bf16 v[98:101], v[130:133], v[206:209], v[98:101]
	v_mfma_f32_16x16x32_bf16 v[90:93], v[146:149], v[206:209], v[90:93]
	v_mfma_f32_16x16x32_bf16 v[82:85], v[130:133], v[214:217], v[82:85]
	v_mfma_f32_16x16x32_bf16 v[74:77], v[146:149], v[214:217], v[74:77]
	v_mfma_f32_16x16x32_bf16 v[126:129], v[134:137], v[194:197], v[126:129]
	v_mfma_f32_16x16x32_bf16 v[122:125], v[150:153], v[194:197], v[122:125]
	v_mfma_f32_16x16x32_bf16 v[114:117], v[134:137], v[202:205], v[114:117]
	v_mfma_f32_16x16x32_bf16 v[106:109], v[150:153], v[202:205], v[106:109]
	v_mfma_f32_16x16x32_bf16 v[98:101], v[134:137], v[210:213], v[98:101]
	v_mfma_f32_16x16x32_bf16 v[90:93], v[150:153], v[210:213], v[90:93]
	v_mfma_f32_16x16x32_bf16 v[82:85], v[134:137], v[218:221], v[82:85]
	v_mfma_f32_16x16x32_bf16 v[74:77], v[150:153], v[218:221], v[74:77]
	s_setprio 0
	s_setprio 1
	v_mfma_f32_16x16x32_bf16 v[118:121], v[154:157], v[190:193], v[118:121]
	v_mfma_f32_16x16x32_bf16 v[110:113], v[178:181], v[190:193], v[110:113]
	v_mfma_f32_16x16x32_bf16 v[102:105], v[154:157], v[198:201], v[102:105]
	v_mfma_f32_16x16x32_bf16 v[94:97], v[178:181], v[198:201], v[94:97]
	v_mfma_f32_16x16x32_bf16 v[86:89], v[154:157], v[206:209], v[86:89]
	v_mfma_f32_16x16x32_bf16 v[78:81], v[178:181], v[206:209], v[78:81]
	v_mfma_f32_16x16x32_bf16 v[70:73], v[154:157], v[214:217], v[70:73]
	v_mfma_f32_16x16x32_bf16 v[66:69], v[178:181], v[214:217], v[66:69]
	v_mfma_f32_16x16x32_bf16 v[118:121], v[174:177], v[194:197], v[118:121]
	v_mfma_f32_16x16x32_bf16 v[110:113], v[182:185], v[194:197], v[110:113]
	v_mfma_f32_16x16x32_bf16 v[102:105], v[174:177], v[202:205], v[102:105]
	v_mfma_f32_16x16x32_bf16 v[94:97], v[182:185], v[202:205], v[94:97]
	s_setprio 3
	s_barrier
	v_mfma_f32_16x16x32_bf16 v[86:89], v[174:177], v[210:213], v[86:89]
	v_mfma_f32_16x16x32_bf16 v[78:81], v[182:185], v[210:213], v[78:81]
	v_mfma_f32_16x16x32_bf16 v[70:73], v[174:177], v[218:221], v[70:73]
	v_mfma_f32_16x16x32_bf16 v[66:69], v[182:185], v[218:221], v[66:69]
	s_setprio 0
	s_add_i32 s50, s71, s54
	v_lshl_add_u64 v[222:223], v[222:223], 0, s[30:31]
	s_mov_b32 m0, s50
	ds_read_b128 v[190:193], v188 offset:49152
	ds_read_b128 v[194:197], v188 offset:50176
	ds_read_b128 v[198:201], v188 offset:51200
	ds_read_b128 v[202:205], v188 offset:52224
	ds_read_b128 v[206:209], v188 offset:53248
	ds_read_b128 v[210:213], v188 offset:54272
	ds_read_b128 v[214:217], v188 offset:55296
	ds_read_b128 v[218:221], v188 offset:56320
	global_load_lds_dwordx4 v[222:223], off
	s_add_i32 m0, s50, 0x2000
	s_add_u32 s48, s48, 0x100080
	v_lshl_add_u64 v[222:223], v[224:225], 0, s[30:31]
	s_addc_u32 s49, s49, 0
	s_add_i32 s50, s72, s54
	global_load_lds_dwordx4 v[222:223], off
	v_lshl_add_u64 v[222:223], s[48:49], 0, v[160:161]
	s_mov_b32 m0, s50
	s_nop 0
	global_load_lds_dwordx4 v[222:223], off
	v_lshl_add_u64 v[222:223], s[48:49], 0, v[164:165]
	s_add_i32 m0, s50, 0x2000
	s_nop 0
	global_load_lds_dwordx4 v[222:223], off
	v_lshl_add_u64 v[222:223], v[226:227], 0, s[30:31]
	s_mov_b32 m0, s60
	s_nop 0
	global_load_lds_dwordx4 v[222:223], off
	v_lshl_add_u64 v[222:223], v[228:229], 0, s[30:31]
	s_mov_b32 m0, s61
	s_nop 0
	global_load_lds_dwordx4 v[222:223], off
	s_waitcnt vmcnt(8)
	s_waitcnt lgkmcnt(0)
	s_barrier
	s_setprio 1
	s_waitcnt lgkmcnt(0)
	v_mfma_f32_16x16x32_bf16 v[62:65], v[130:133], v[190:193], v[62:65]
	v_mfma_f32_16x16x32_bf16 v[58:61], v[146:149], v[190:193], v[58:61]
	v_mfma_f32_16x16x32_bf16 v[50:53], v[130:133], v[198:201], v[50:53]
	v_mfma_f32_16x16x32_bf16 v[42:45], v[146:149], v[198:201], v[42:45]
	v_mfma_f32_16x16x32_bf16 v[34:37], v[130:133], v[206:209], v[34:37]
	v_mfma_f32_16x16x32_bf16 v[26:29], v[146:149], v[206:209], v[26:29]
	v_mfma_f32_16x16x32_bf16 v[18:21], v[130:133], v[214:217], v[18:21]
	v_mfma_f32_16x16x32_bf16 v[10:13], v[146:149], v[214:217], v[10:13]
	v_mfma_f32_16x16x32_bf16 v[62:65], v[134:137], v[194:197], v[62:65]
	v_mfma_f32_16x16x32_bf16 v[58:61], v[150:153], v[194:197], v[58:61]
	v_mfma_f32_16x16x32_bf16 v[50:53], v[134:137], v[202:205], v[50:53]
	v_mfma_f32_16x16x32_bf16 v[42:45], v[150:153], v[202:205], v[42:45]
	v_mfma_f32_16x16x32_bf16 v[34:37], v[134:137], v[210:213], v[34:37]
	v_mfma_f32_16x16x32_bf16 v[26:29], v[150:153], v[210:213], v[26:29]
	v_mfma_f32_16x16x32_bf16 v[18:21], v[134:137], v[218:221], v[18:21]
	v_mfma_f32_16x16x32_bf16 v[10:13], v[150:153], v[218:221], v[10:13]
	s_setprio 0
	s_setprio 1
	v_mfma_f32_16x16x32_bf16 v[54:57], v[154:157], v[190:193], v[54:57]
	v_mfma_f32_16x16x32_bf16 v[46:49], v[178:181], v[190:193], v[46:49]
	v_mfma_f32_16x16x32_bf16 v[38:41], v[154:157], v[198:201], v[38:41]
	v_mfma_f32_16x16x32_bf16 v[30:33], v[178:181], v[198:201], v[30:33]
	v_mfma_f32_16x16x32_bf16 v[22:25], v[154:157], v[206:209], v[22:25]
	v_mfma_f32_16x16x32_bf16 v[14:17], v[178:181], v[206:209], v[14:17]
	v_mfma_f32_16x16x32_bf16 v[6:9], v[154:157], v[214:217], v[6:9]
	v_mfma_f32_16x16x32_bf16 v[2:5], v[178:181], v[214:217], v[2:5]
	v_mfma_f32_16x16x32_bf16 v[54:57], v[174:177], v[194:197], v[54:57]
	v_mfma_f32_16x16x32_bf16 v[46:49], v[182:185], v[194:197], v[46:49]
	v_mfma_f32_16x16x32_bf16 v[38:41], v[174:177], v[202:205], v[38:41]
	v_mfma_f32_16x16x32_bf16 v[30:33], v[182:185], v[202:205], v[30:33]
	s_setprio 3
	s_barrier
	v_mfma_f32_16x16x32_bf16 v[22:25], v[174:177], v[210:213], v[22:25]
	v_mfma_f32_16x16x32_bf16 v[14:17], v[182:185], v[210:213], v[14:17]
	v_mfma_f32_16x16x32_bf16 v[6:9], v[174:177], v[218:221], v[6:9]
	v_mfma_f32_16x16x32_bf16 v[2:5], v[182:185], v[218:221], v[2:5]
	s_setprio 0
	s_add_i32 s70, s70, 2
	s_add_u32 s46, s46, 0x100
	s_addc_u32 s47, s47, 0
	s_cmp_gt_u32 s70, 61
	s_cbranch_scc1 .LBB0_543

.LBB0_618:
	ds_read_b128 v[146:149], v154
	ds_read_b128 v[158:161], v154 offset:1024
	ds_read_b128 v[162:165], v154 offset:2048
	ds_read_b128 v[166:169], v154 offset:3072
	ds_read_b128 v[170:173], v155
	ds_read_b128 v[174:177], v155 offset:1024
	ds_read_b128 v[178:181], v155 offset:2048
	ds_read_b128 v[182:185], v155 offset:3072
	s_add_u32 s48, s46, 0xfff00080
	s_addc_u32 s49, s47, -1
	s_cmp_eq_u32 s68, 60
	s_cselect_b32 s51, s39, s49
	s_cselect_b32 s50, s64, s48
	s_cselect_b32 s49, s37, s67
	s_cselect_b32 s48, s65, s66
	v_lshl_add_u64 v[150:151], s[46:47], 0, v[138:139]
	s_add_i32 m0, s45, 0xc000
	ds_read_b128 v[186:189], v156
	ds_read_b128 v[190:193], v156 offset:1024
	ds_read_b128 v[194:197], v156 offset:2048
	ds_read_b128 v[198:201], v156 offset:3072
	ds_read_b128 v[202:205], v156 offset:4096
	ds_read_b128 v[206:209], v156 offset:5120
	ds_read_b128 v[210:213], v156 offset:6144
	ds_read_b128 v[214:217], v156 offset:7168
	global_load_lds_dwordx4 v[150:151], off
	v_lshl_add_u64 v[150:151], s[46:47], 0, v[140:141]
	s_add_i32 m0, s45, 0xe000
	s_nop 0
	global_load_lds_dwordx4 v[150:151], off
	s_waitcnt vmcnt(8)
	s_waitcnt lgkmcnt(0)
	s_barrier
	s_setprio 1
	s_waitcnt lgkmcnt(0)
	v_mfma_f32_16x16x32_bf16 v[126:129], v[146:149], v[186:189], v[126:129]
	v_mfma_f32_16x16x32_bf16 v[122:125], v[162:165], v[186:189], v[122:125]
	v_mfma_f32_16x16x32_bf16 v[118:121], v[146:149], v[194:197], v[118:121]
	v_mfma_f32_16x16x32_bf16 v[114:117], v[162:165], v[194:197], v[114:117]
	v_mfma_f32_16x16x32_bf16 v[102:105], v[146:149], v[202:205], v[102:105]
	v_mfma_f32_16x16x32_bf16 v[98:101], v[162:165], v[202:205], v[98:101]
	v_mfma_f32_16x16x32_bf16 v[86:89], v[146:149], v[210:213], v[86:89]
	v_mfma_f32_16x16x32_bf16 v[78:81], v[162:165], v[210:213], v[78:81]
	v_mfma_f32_16x16x32_bf16 v[126:129], v[158:161], v[190:193], v[126:129]
	v_mfma_f32_16x16x32_bf16 v[122:125], v[166:169], v[190:193], v[122:125]
	v_mfma_f32_16x16x32_bf16 v[118:121], v[158:161], v[198:201], v[118:121]
	v_mfma_f32_16x16x32_bf16 v[114:117], v[166:169], v[198:201], v[114:117]
	v_mfma_f32_16x16x32_bf16 v[102:105], v[158:161], v[206:209], v[102:105]
	v_mfma_f32_16x16x32_bf16 v[98:101], v[166:169], v[206:209], v[98:101]
	v_mfma_f32_16x16x32_bf16 v[86:89], v[158:161], v[214:217], v[86:89]
	v_mfma_f32_16x16x32_bf16 v[78:81], v[166:169], v[214:217], v[78:81]
	s_setprio 0
	s_setprio 1
	v_mfma_f32_16x16x32_bf16 v[110:113], v[170:173], v[186:189], v[110:113]
	v_mfma_f32_16x16x32_bf16 v[106:109], v[178:181], v[186:189], v[106:109]
	v_mfma_f32_16x16x32_bf16 v[94:97], v[170:173], v[194:197], v[94:97]
	v_mfma_f32_16x16x32_bf16 v[90:93], v[178:181], v[194:197], v[90:93]
	v_mfma_f32_16x16x32_bf16 v[82:85], v[170:173], v[202:205], v[82:85]
	v_mfma_f32_16x16x32_bf16 v[74:77], v[178:181], v[202:205], v[74:77]
	v_mfma_f32_16x16x32_bf16 v[70:73], v[170:173], v[210:213], v[70:73]
	v_mfma_f32_16x16x32_bf16 v[66:69], v[178:181], v[210:213], v[66:69]
	v_mfma_f32_16x16x32_bf16 v[110:113], v[174:177], v[190:193], v[110:113]
	v_mfma_f32_16x16x32_bf16 v[106:109], v[182:185], v[190:193], v[106:109]
	v_mfma_f32_16x16x32_bf16 v[94:97], v[174:177], v[198:201], v[94:97]
	v_mfma_f32_16x16x32_bf16 v[90:93], v[182:185], v[198:201], v[90:93]
	s_setprio 3
	s_barrier
	v_mfma_f32_16x16x32_bf16 v[82:85], v[174:177], v[206:209], v[82:85]
	v_mfma_f32_16x16x32_bf16 v[74:77], v[182:185], v[206:209], v[74:77]
	v_mfma_f32_16x16x32_bf16 v[70:73], v[174:177], v[214:217], v[70:73]
	v_mfma_f32_16x16x32_bf16 v[66:69], v[182:185], v[214:217], v[66:69]
	s_setprio 0
	s_add_i32 s69, s61, s53
	v_lshl_add_u64 v[150:151], s[48:49], 0, v[132:133]
	s_mov_b32 m0, s69
	ds_read_b128 v[186:189], v156 offset:16384
	ds_read_b128 v[190:193], v156 offset:17408
	ds_read_b128 v[194:197], v156 offset:18432
	ds_read_b128 v[198:201], v156 offset:19456
	ds_read_b128 v[202:205], v156 offset:20480
	ds_read_b128 v[206:209], v156 offset:21504
	ds_read_b128 v[210:213], v156 offset:22528
	ds_read_b128 v[214:217], v156 offset:23552
	global_load_lds_dwordx4 v[150:151], off
	s_add_i32 m0, s69, 0x2000
	s_add_u32 s70, s48, 0x100000
	v_lshl_add_u64 v[218:219], s[48:49], 0, v[136:137]
	s_addc_u32 s71, s49, 0
	s_add_i32 s69, s62, s53
	global_load_lds_dwordx4 v[218:219], off
	v_lshl_add_u64 v[220:221], s[70:71], 0, v[132:133]
	s_mov_b32 m0, s69
	v_lshl_add_u64 v[222:223], s[50:51], 0, v[134:135]
	global_load_lds_dwordx4 v[220:221], off
	v_lshl_add_u64 v[220:221], s[70:71], 0, v[136:137]
	s_add_i32 m0, s69, 0x2000
	s_nop 0
	global_load_lds_dwordx4 v[220:221], off
	v_lshl_add_u64 v[220:221], s[50:51], 0, v[130:131]
	s_mov_b32 m0, s45
	s_nop 0
	global_load_lds_dwordx4 v[220:221], off
	s_mov_b32 m0, s54
	s_nop 0
	global_load_lds_dwordx4 v[222:223], off
	s_waitcnt vmcnt(8)
	s_waitcnt lgkmcnt(0)
	s_barrier
	s_setprio 1
	s_waitcnt lgkmcnt(0)
	v_mfma_f32_16x16x32_bf16 v[62:65], v[146:149], v[186:189], v[62:65]
	v_mfma_f32_16x16x32_bf16 v[58:61], v[162:165], v[186:189], v[58:61]
	v_mfma_f32_16x16x32_bf16 v[50:53], v[146:149], v[194:197], v[50:53]
	v_mfma_f32_16x16x32_bf16 v[42:45], v[162:165], v[194:197], v[42:45]
	v_mfma_f32_16x16x32_bf16 v[38:41], v[146:149], v[202:205], v[38:41]
	v_mfma_f32_16x16x32_bf16 v[30:33], v[162:165], v[202:205], v[30:33]
	v_mfma_f32_16x16x32_bf16 v[22:25], v[146:149], v[210:213], v[22:25]
	v_mfma_f32_16x16x32_bf16 v[14:17], v[162:165], v[210:213], v[14:17]
	v_mfma_f32_16x16x32_bf16 v[62:65], v[158:161], v[190:193], v[62:65]
	v_mfma_f32_16x16x32_bf16 v[58:61], v[166:169], v[190:193], v[58:61]
	v_mfma_f32_16x16x32_bf16 v[50:53], v[158:161], v[198:201], v[50:53]
	v_mfma_f32_16x16x32_bf16 v[42:45], v[166:169], v[198:201], v[42:45]
	v_mfma_f32_16x16x32_bf16 v[38:41], v[158:161], v[206:209], v[38:41]
	v_mfma_f32_16x16x32_bf16 v[30:33], v[166:169], v[206:209], v[30:33]
	v_mfma_f32_16x16x32_bf16 v[22:25], v[158:161], v[214:217], v[22:25]
	v_mfma_f32_16x16x32_bf16 v[14:17], v[166:169], v[214:217], v[14:17]
	s_setprio 0
	s_setprio 1
	v_mfma_f32_16x16x32_bf16 v[54:57], v[170:173], v[186:189], v[54:57]
	v_mfma_f32_16x16x32_bf16 v[46:49], v[178:181], v[186:189], v[46:49]
	v_mfma_f32_16x16x32_bf16 v[34:37], v[170:173], v[194:197], v[34:37]
	v_mfma_f32_16x16x32_bf16 v[26:29], v[178:181], v[194:197], v[26:29]
	v_mfma_f32_16x16x32_bf16 v[18:21], v[170:173], v[202:205], v[18:21]
	v_mfma_f32_16x16x32_bf16 v[10:13], v[178:181], v[202:205], v[10:13]
	v_mfma_f32_16x16x32_bf16 v[6:9], v[170:173], v[210:213], v[6:9]
	v_mfma_f32_16x16x32_bf16 v[2:5], v[178:181], v[210:213], v[2:5]
	v_mfma_f32_16x16x32_bf16 v[54:57], v[174:177], v[190:193], v[54:57]
	v_mfma_f32_16x16x32_bf16 v[46:49], v[182:185], v[190:193], v[46:49]
	v_mfma_f32_16x16x32_bf16 v[34:37], v[174:177], v[198:201], v[34:37]
	v_mfma_f32_16x16x32_bf16 v[26:29], v[182:185], v[198:201], v[26:29]
	s_setprio 3
	s_barrier
	v_mfma_f32_16x16x32_bf16 v[18:21], v[174:177], v[206:209], v[18:21]
	v_mfma_f32_16x16x32_bf16 v[10:13], v[182:185], v[206:209], v[10:13]
	v_mfma_f32_16x16x32_bf16 v[6:9], v[174:177], v[214:217], v[6:9]
	v_mfma_f32_16x16x32_bf16 v[2:5], v[182:185], v[214:217], v[2:5]
	s_setprio 0
	s_add_i32 s69, 0, 0x18000
	v_add_u32_e32 v157, s69, v152
	s_add_i32 s70, 0, 0x1c000
	ds_read_b128 v[146:149], v157
	ds_read_b128 v[158:161], v157 offset:1024
	ds_read_b128 v[162:165], v157 offset:2048
	ds_read_b128 v[166:169], v157 offset:3072
	v_add_u32_e32 v157, s70, v152
	ds_read_b128 v[170:173], v157
	ds_read_b128 v[174:177], v157 offset:1024
	ds_read_b128 v[178:181], v157 offset:2048
	ds_read_b128 v[182:185], v157 offset:3072
	s_add_u32 s50, s50, 0x100000
	s_addc_u32 s51, s51, 0
	s_mov_b32 m0, s55
	v_lshl_add_u64 v[224:225], s[50:51], 0, v[130:131]
	ds_read_b128 v[186:189], v156 offset:32768
	ds_read_b128 v[190:193], v156 offset:33792
	ds_read_b128 v[194:197], v156 offset:34816
	ds_read_b128 v[198:201], v156 offset:35840
	ds_read_b128 v[202:205], v156 offset:36864
	ds_read_b128 v[206:209], v156 offset:37888
	ds_read_b128 v[210:213], v156 offset:38912
	ds_read_b128 v[214:217], v156 offset:39936
	global_load_lds_dwordx4 v[224:225], off
	v_lshl_add_u64 v[224:225], s[50:51], 0, v[134:135]
	s_mov_b32 m0, s56
	s_nop 0
	global_load_lds_dwordx4 v[224:225], off
	s_waitcnt vmcnt(8)
	s_waitcnt lgkmcnt(0)
	s_barrier
	s_setprio 1
	s_waitcnt lgkmcnt(0)
	v_mfma_f32_16x16x32_bf16 v[126:129], v[146:149], v[186:189], v[126:129]
	v_mfma_f32_16x16x32_bf16 v[122:125], v[162:165], v[186:189], v[122:125]
	v_mfma_f32_16x16x32_bf16 v[118:121], v[146:149], v[194:197], v[118:121]
	v_mfma_f32_16x16x32_bf16 v[114:117], v[162:165], v[194:197], v[114:117]
	v_mfma_f32_16x16x32_bf16 v[102:105], v[146:149], v[202:205], v[102:105]
	v_mfma_f32_16x16x32_bf16 v[98:101], v[162:165], v[202:205], v[98:101]
	v_mfma_f32_16x16x32_bf16 v[86:89], v[146:149], v[210:213], v[86:89]
	v_mfma_f32_16x16x32_bf16 v[78:81], v[162:165], v[210:213], v[78:81]
	v_mfma_f32_16x16x32_bf16 v[126:129], v[158:161], v[190:193], v[126:129]
	v_mfma_f32_16x16x32_bf16 v[122:125], v[166:169], v[190:193], v[122:125]
	v_mfma_f32_16x16x32_bf16 v[118:121], v[158:161], v[198:201], v[118:121]
	v_mfma_f32_16x16x32_bf16 v[114:117], v[166:169], v[198:201], v[114:117]
	v_mfma_f32_16x16x32_bf16 v[102:105], v[158:161], v[206:209], v[102:105]
	v_mfma_f32_16x16x32_bf16 v[98:101], v[166:169], v[206:209], v[98:101]
	v_mfma_f32_16x16x32_bf16 v[86:89], v[158:161], v[214:217], v[86:89]
	v_mfma_f32_16x16x32_bf16 v[78:81], v[166:169], v[214:217], v[78:81]
	s_setprio 0
	s_setprio 1
	v_mfma_f32_16x16x32_bf16 v[110:113], v[170:173], v[186:189], v[110:113]
	v_mfma_f32_16x16x32_bf16 v[106:109], v[178:181], v[186:189], v[106:109]
	v_mfma_f32_16x16x32_bf16 v[94:97], v[170:173], v[194:197], v[94:97]
	v_mfma_f32_16x16x32_bf16 v[90:93], v[178:181], v[194:197], v[90:93]
	v_mfma_f32_16x16x32_bf16 v[82:85], v[170:173], v[202:205], v[82:85]
	v_mfma_f32_16x16x32_bf16 v[74:77], v[178:181], v[202:205], v[74:77]
	v_mfma_f32_16x16x32_bf16 v[70:73], v[170:173], v[210:213], v[70:73]
	v_mfma_f32_16x16x32_bf16 v[66:69], v[178:181], v[210:213], v[66:69]
	v_mfma_f32_16x16x32_bf16 v[110:113], v[174:177], v[190:193], v[110:113]
	v_mfma_f32_16x16x32_bf16 v[106:109], v[182:185], v[190:193], v[106:109]
	v_mfma_f32_16x16x32_bf16 v[94:97], v[174:177], v[198:201], v[94:97]
	v_mfma_f32_16x16x32_bf16 v[90:93], v[182:185], v[198:201], v[90:93]
	s_setprio 3
	s_barrier
	v_mfma_f32_16x16x32_bf16 v[82:85], v[174:177], v[206:209], v[82:85]
	v_mfma_f32_16x16x32_bf16 v[74:77], v[182:185], v[206:209], v[74:77]
	v_mfma_f32_16x16x32_bf16 v[70:73], v[174:177], v[214:217], v[70:73]
	v_mfma_f32_16x16x32_bf16 v[66:69], v[182:185], v[214:217], v[66:69]
	s_setprio 0
	s_add_i32 s50, s69, s53
	v_lshl_add_u64 v[150:151], v[150:151], 0, s[28:29]
	s_mov_b32 m0, s50
	ds_read_b128 v[186:189], v156 offset:49152
	ds_read_b128 v[190:193], v156 offset:50176
	ds_read_b128 v[194:197], v156 offset:51200
	ds_read_b128 v[198:201], v156 offset:52224
	ds_read_b128 v[202:205], v156 offset:53248
	ds_read_b128 v[206:209], v156 offset:54272
	ds_read_b128 v[210:213], v156 offset:55296
	ds_read_b128 v[214:217], v156 offset:56320
	global_load_lds_dwordx4 v[150:151], off
	s_add_i32 m0, s50, 0x2000
	s_add_u32 s48, s48, 0x100080
	v_lshl_add_u64 v[150:151], v[218:219], 0, s[28:29]
	s_addc_u32 s49, s49, 0
	s_add_i32 s50, s70, s53
	global_load_lds_dwordx4 v[150:151], off
	v_lshl_add_u64 v[150:151], s[48:49], 0, v[132:133]
	s_mov_b32 m0, s50
	s_nop 0
	global_load_lds_dwordx4 v[150:151], off
	v_lshl_add_u64 v[150:151], s[48:49], 0, v[136:137]
	s_add_i32 m0, s50, 0x2000
	s_nop 0
	global_load_lds_dwordx4 v[150:151], off
	v_lshl_add_u64 v[150:151], v[220:221], 0, s[28:29]
	s_mov_b32 m0, s58
	s_nop 0
	global_load_lds_dwordx4 v[150:151], off
	v_lshl_add_u64 v[150:151], v[222:223], 0, s[28:29]
	s_mov_b32 m0, s59
	s_nop 0
	global_load_lds_dwordx4 v[150:151], off
	s_waitcnt vmcnt(8)
	s_waitcnt lgkmcnt(0)
	s_barrier
	s_setprio 1
	s_waitcnt lgkmcnt(0)
	v_mfma_f32_16x16x32_bf16 v[62:65], v[146:149], v[186:189], v[62:65]
	v_mfma_f32_16x16x32_bf16 v[58:61], v[162:165], v[186:189], v[58:61]
	v_mfma_f32_16x16x32_bf16 v[50:53], v[146:149], v[194:197], v[50:53]
	v_mfma_f32_16x16x32_bf16 v[42:45], v[162:165], v[194:197], v[42:45]
	v_mfma_f32_16x16x32_bf16 v[38:41], v[146:149], v[202:205], v[38:41]
	v_mfma_f32_16x16x32_bf16 v[30:33], v[162:165], v[202:205], v[30:33]
	v_mfma_f32_16x16x32_bf16 v[22:25], v[146:149], v[210:213], v[22:25]
	v_mfma_f32_16x16x32_bf16 v[14:17], v[162:165], v[210:213], v[14:17]
	v_mfma_f32_16x16x32_bf16 v[62:65], v[158:161], v[190:193], v[62:65]
	v_mfma_f32_16x16x32_bf16 v[58:61], v[166:169], v[190:193], v[58:61]
	v_mfma_f32_16x16x32_bf16 v[50:53], v[158:161], v[198:201], v[50:53]
	v_mfma_f32_16x16x32_bf16 v[42:45], v[166:169], v[198:201], v[42:45]
	v_mfma_f32_16x16x32_bf16 v[38:41], v[158:161], v[206:209], v[38:41]
	v_mfma_f32_16x16x32_bf16 v[30:33], v[166:169], v[206:209], v[30:33]
	v_mfma_f32_16x16x32_bf16 v[22:25], v[158:161], v[214:217], v[22:25]
	v_mfma_f32_16x16x32_bf16 v[14:17], v[166:169], v[214:217], v[14:17]
	s_setprio 0
	s_setprio 1
	v_mfma_f32_16x16x32_bf16 v[54:57], v[170:173], v[186:189], v[54:57]
	v_mfma_f32_16x16x32_bf16 v[46:49], v[178:181], v[186:189], v[46:49]
	v_mfma_f32_16x16x32_bf16 v[34:37], v[170:173], v[194:197], v[34:37]
	v_mfma_f32_16x16x32_bf16 v[26:29], v[178:181], v[194:197], v[26:29]
	v_mfma_f32_16x16x32_bf16 v[18:21], v[170:173], v[202:205], v[18:21]
	v_mfma_f32_16x16x32_bf16 v[10:13], v[178:181], v[202:205], v[10:13]
	v_mfma_f32_16x16x32_bf16 v[6:9], v[170:173], v[210:213], v[6:9]
	v_mfma_f32_16x16x32_bf16 v[2:5], v[178:181], v[210:213], v[2:5]
	v_mfma_f32_16x16x32_bf16 v[54:57], v[174:177], v[190:193], v[54:57]
	v_mfma_f32_16x16x32_bf16 v[46:49], v[182:185], v[190:193], v[46:49]
	v_mfma_f32_16x16x32_bf16 v[34:37], v[174:177], v[198:201], v[34:37]
	v_mfma_f32_16x16x32_bf16 v[26:29], v[182:185], v[198:201], v[26:29]
	s_setprio 3
	s_barrier
	v_mfma_f32_16x16x32_bf16 v[18:21], v[174:177], v[206:209], v[18:21]
	v_mfma_f32_16x16x32_bf16 v[10:13], v[182:185], v[206:209], v[10:13]
	v_mfma_f32_16x16x32_bf16 v[6:9], v[174:177], v[214:217], v[6:9]
	v_mfma_f32_16x16x32_bf16 v[2:5], v[182:185], v[214:217], v[2:5]
	s_setprio 0
	s_add_i32 s68, s68, 2
	s_add_u32 s46, s46, 0x100
	s_addc_u32 s47, s47, 0
	s_add_u32 s66, s66, 0x100
	s_addc_u32 s67, s67, 0
	s_cmp_gt_u32 s68, 61
	s_cbranch_scc0 .LBB0_618
	s_and_b64 vcc, exec, s[30:31]
	s_cbranch_vccz .LBB0_621
	s_barrier

.LBB0_743:
	ds_read_b128 v[130:133], v197
	ds_read_b128 v[134:137], v197 offset:1024
	ds_read_b128 v[138:141], v197 offset:2048
	ds_read_b128 v[142:145], v197 offset:3072
	ds_read_b128 v[146:149], v198
	ds_read_b128 v[150:153], v198 offset:1024
	ds_read_b128 v[154:157], v198 offset:2048
	ds_read_b128 v[158:161], v198 offset:3072
	s_add_u32 s72, s70, 0xfff00080
	s_addc_u32 s73, s71, -1
	s_cmp_eq_u32 s95, 60
	s_cselect_b32 s75, s61, s73
	s_cselect_b32 s74, s67, s72
	s_cselect_b32 s73, s59, s94
	s_cselect_b32 s72, s69, s93
	v_lshl_add_u64 v[184:185], s[70:71], 0, v[176:177]
	s_add_i32 m0, s78, 0xc000
	ds_read_b128 v[200:203], v199
	ds_read_b128 v[204:207], v199 offset:1024
	ds_read_b128 v[208:211], v199 offset:2048
	ds_read_b128 v[212:215], v199 offset:3072
	ds_read_b128 v[216:219], v199 offset:4096
	ds_read_b128 v[220:223], v199 offset:5120
	ds_read_b128 v[224:227], v199 offset:6144
	ds_read_b128 v[228:231], v199 offset:7168
	global_load_lds_dwordx4 v[184:185], off
	v_lshl_add_u64 v[184:185], s[70:71], 0, v[178:179]
	s_add_i32 m0, s78, 0xe000
	s_nop 0
	global_load_lds_dwordx4 v[184:185], off
	s_waitcnt vmcnt(8)
	s_waitcnt lgkmcnt(0)
	s_barrier
	s_setprio 1
	s_waitcnt lgkmcnt(0)
	v_mfma_f32_16x16x32_bf16 v[102:105], v[130:133], v[200:203], v[102:105]
	v_mfma_f32_16x16x32_bf16 v[98:101], v[138:141], v[200:203], v[98:101]
	v_mfma_f32_16x16x32_bf16 v[110:113], v[130:133], v[208:211], v[110:113]
	v_mfma_f32_16x16x32_bf16 v[106:109], v[138:141], v[208:211], v[106:109]
	v_mfma_f32_16x16x32_bf16 v[118:121], v[130:133], v[216:219], v[118:121]
	v_mfma_f32_16x16x32_bf16 v[114:117], v[138:141], v[216:219], v[114:117]
	v_mfma_f32_16x16x32_bf16 v[126:129], v[130:133], v[224:227], v[126:129]
	v_mfma_f32_16x16x32_bf16 v[122:125], v[138:141], v[224:227], v[122:125]
	v_mfma_f32_16x16x32_bf16 v[102:105], v[134:137], v[204:207], v[102:105]
	v_mfma_f32_16x16x32_bf16 v[98:101], v[142:145], v[204:207], v[98:101]
	v_mfma_f32_16x16x32_bf16 v[110:113], v[134:137], v[212:215], v[110:113]
	v_mfma_f32_16x16x32_bf16 v[106:109], v[142:145], v[212:215], v[106:109]
	v_mfma_f32_16x16x32_bf16 v[118:121], v[134:137], v[220:223], v[118:121]
	v_mfma_f32_16x16x32_bf16 v[114:117], v[142:145], v[220:223], v[114:117]
	v_mfma_f32_16x16x32_bf16 v[126:129], v[134:137], v[228:231], v[126:129]
	v_mfma_f32_16x16x32_bf16 v[122:125], v[142:145], v[228:231], v[122:125]
	s_setprio 0
	s_setprio 1
	v_mfma_f32_16x16x32_bf16 v[38:41], v[146:149], v[200:203], v[38:41]
	v_mfma_f32_16x16x32_bf16 v[34:37], v[154:157], v[200:203], v[34:37]
	v_mfma_f32_16x16x32_bf16 v[46:49], v[146:149], v[208:211], v[46:49]
	v_mfma_f32_16x16x32_bf16 v[42:45], v[154:157], v[208:211], v[42:45]
	v_mfma_f32_16x16x32_bf16 v[54:57], v[146:149], v[216:219], v[54:57]
	v_mfma_f32_16x16x32_bf16 v[50:53], v[154:157], v[216:219], v[50:53]
	v_mfma_f32_16x16x32_bf16 v[62:65], v[146:149], v[224:227], v[62:65]
	v_mfma_f32_16x16x32_bf16 v[58:61], v[154:157], v[224:227], v[58:61]
	v_mfma_f32_16x16x32_bf16 v[38:41], v[150:153], v[204:207], v[38:41]
	v_mfma_f32_16x16x32_bf16 v[34:37], v[158:161], v[204:207], v[34:37]
	v_mfma_f32_16x16x32_bf16 v[46:49], v[150:153], v[212:215], v[46:49]
	v_mfma_f32_16x16x32_bf16 v[42:45], v[158:161], v[212:215], v[42:45]
	s_setprio 3
	s_barrier
	v_mfma_f32_16x16x32_bf16 v[54:57], v[150:153], v[220:223], v[54:57]
	v_mfma_f32_16x16x32_bf16 v[50:53], v[158:161], v[220:223], v[50:53]
	v_mfma_f32_16x16x32_bf16 v[62:65], v[150:153], v[228:231], v[62:65]
	v_mfma_f32_16x16x32_bf16 v[58:61], v[158:161], v[228:231], v[58:61]
	s_setprio 0
	s_add_i32 s96, s90, s77
	v_lshl_add_u64 v[184:185], s[72:73], 0, v[164:165]
	s_mov_b32 m0, s96
	ds_read_b128 v[200:203], v199 offset:16384
	ds_read_b128 v[204:207], v199 offset:17408
	ds_read_b128 v[208:211], v199 offset:18432
	ds_read_b128 v[212:215], v199 offset:19456
	ds_read_b128 v[216:219], v199 offset:20480
	ds_read_b128 v[220:223], v199 offset:21504
	ds_read_b128 v[224:227], v199 offset:22528
	ds_read_b128 v[228:231], v199 offset:23552
	global_load_lds_dwordx4 v[184:185], off
	s_add_i32 m0, s96, 0x2000
	s_add_u32 s96, s72, 0x100000
	v_lshl_add_u64 v[232:233], s[72:73], 0, v[168:169]
	s_addc_u32 s97, s73, 0
	s_add_i32 vcc_lo, s91, s77
	global_load_lds_dwordx4 v[232:233], off
	v_lshl_add_u64 v[234:235], s[96:97], 0, v[164:165]
	s_mov_b32 m0, vcc_lo
	v_lshl_add_u64 v[236:237], s[74:75], 0, v[166:167]
	global_load_lds_dwordx4 v[234:235], off
	v_lshl_add_u64 v[234:235], s[96:97], 0, v[168:169]
	s_add_i32 m0, vcc_lo, 0x2000
	s_nop 0
	global_load_lds_dwordx4 v[234:235], off
	v_lshl_add_u64 v[234:235], s[74:75], 0, v[162:163]
	s_mov_b32 m0, s78
	s_nop 0
	global_load_lds_dwordx4 v[234:235], off
	s_mov_b32 m0, s79
	s_nop 0
	global_load_lds_dwordx4 v[236:237], off
	s_waitcnt vmcnt(8)
	s_waitcnt lgkmcnt(0)
	s_barrier
	s_setprio 1
	s_waitcnt lgkmcnt(0)
	v_mfma_f32_16x16x32_bf16 v[70:73], v[130:133], v[200:203], v[70:73]
	v_mfma_f32_16x16x32_bf16 v[66:69], v[138:141], v[200:203], v[66:69]
	v_mfma_f32_16x16x32_bf16 v[78:81], v[130:133], v[208:211], v[78:81]
	v_mfma_f32_16x16x32_bf16 v[74:77], v[138:141], v[208:211], v[74:77]
	v_mfma_f32_16x16x32_bf16 v[86:89], v[130:133], v[216:219], v[86:89]
	v_mfma_f32_16x16x32_bf16 v[82:85], v[138:141], v[216:219], v[82:85]
	v_mfma_f32_16x16x32_bf16 v[94:97], v[130:133], v[224:227], v[94:97]
	v_mfma_f32_16x16x32_bf16 v[90:93], v[138:141], v[224:227], v[90:93]
	v_mfma_f32_16x16x32_bf16 v[70:73], v[134:137], v[204:207], v[70:73]
	v_mfma_f32_16x16x32_bf16 v[66:69], v[142:145], v[204:207], v[66:69]
	v_mfma_f32_16x16x32_bf16 v[78:81], v[134:137], v[212:215], v[78:81]
	v_mfma_f32_16x16x32_bf16 v[74:77], v[142:145], v[212:215], v[74:77]
	v_mfma_f32_16x16x32_bf16 v[86:89], v[134:137], v[220:223], v[86:89]
	v_mfma_f32_16x16x32_bf16 v[82:85], v[142:145], v[220:223], v[82:85]
	v_mfma_f32_16x16x32_bf16 v[94:97], v[134:137], v[228:231], v[94:97]
	v_mfma_f32_16x16x32_bf16 v[90:93], v[142:145], v[228:231], v[90:93]
	s_setprio 0
	s_setprio 1
	v_mfma_f32_16x16x32_bf16 v[6:9], v[146:149], v[200:203], v[6:9]
	v_mfma_f32_16x16x32_bf16 v[2:5], v[154:157], v[200:203], v[2:5]
	v_mfma_f32_16x16x32_bf16 v[14:17], v[146:149], v[208:211], v[14:17]
	v_mfma_f32_16x16x32_bf16 v[10:13], v[154:157], v[208:211], v[10:13]
	v_mfma_f32_16x16x32_bf16 v[22:25], v[146:149], v[216:219], v[22:25]
	v_mfma_f32_16x16x32_bf16 v[18:21], v[154:157], v[216:219], v[18:21]
	v_mfma_f32_16x16x32_bf16 v[30:33], v[146:149], v[224:227], v[30:33]
	v_mfma_f32_16x16x32_bf16 v[26:29], v[154:157], v[224:227], v[26:29]
	v_mfma_f32_16x16x32_bf16 v[6:9], v[150:153], v[204:207], v[6:9]
	v_mfma_f32_16x16x32_bf16 v[2:5], v[158:161], v[204:207], v[2:5]
	v_mfma_f32_16x16x32_bf16 v[14:17], v[150:153], v[212:215], v[14:17]
	v_mfma_f32_16x16x32_bf16 v[10:13], v[158:161], v[212:215], v[10:13]
	s_setprio 3
	s_barrier
	v_mfma_f32_16x16x32_bf16 v[22:25], v[150:153], v[220:223], v[22:25]
	v_mfma_f32_16x16x32_bf16 v[18:21], v[158:161], v[220:223], v[18:21]
	v_mfma_f32_16x16x32_bf16 v[30:33], v[150:153], v[228:231], v[30:33]
	v_mfma_f32_16x16x32_bf16 v[26:29], v[158:161], v[228:231], v[26:29]
	s_setprio 0
	s_add_i32 s96, 0, 0x18000
	s_add_i32 s97, 0, 0x1c000
	v_add_u32_e32 v142, s96, v173
	v_add_u32_e32 v158, s97, v173
	ds_read_b128 v[130:133], v142
	ds_read_b128 v[134:137], v142 offset:1024
	ds_read_b128 v[138:141], v142 offset:2048
	ds_read_b128 v[142:145], v142 offset:3072
	ds_read_b128 v[146:149], v158
	ds_read_b128 v[150:153], v158 offset:1024
	ds_read_b128 v[154:157], v158 offset:2048
	ds_read_b128 v[158:161], v158 offset:3072
	s_add_u32 s74, s74, 0x100000
	s_addc_u32 s75, s75, 0
	s_mov_b32 m0, s80
	v_lshl_add_u64 v[238:239], s[74:75], 0, v[162:163]
	ds_read_b128 v[200:203], v199 offset:32768
	ds_read_b128 v[204:207], v199 offset:33792
	ds_read_b128 v[208:211], v199 offset:34816
	ds_read_b128 v[212:215], v199 offset:35840
	ds_read_b128 v[216:219], v199 offset:36864
	ds_read_b128 v[220:223], v199 offset:37888
	ds_read_b128 v[224:227], v199 offset:38912
	ds_read_b128 v[228:231], v199 offset:39936
	global_load_lds_dwordx4 v[238:239], off
	v_lshl_add_u64 v[238:239], s[74:75], 0, v[166:167]
	s_mov_b32 m0, s81
	s_nop 0
	global_load_lds_dwordx4 v[238:239], off
	s_waitcnt vmcnt(8)
	s_waitcnt lgkmcnt(0)
	s_barrier
	s_setprio 1
	s_waitcnt lgkmcnt(0)
	v_mfma_f32_16x16x32_bf16 v[102:105], v[130:133], v[200:203], v[102:105]
	v_mfma_f32_16x16x32_bf16 v[98:101], v[138:141], v[200:203], v[98:101]
	v_mfma_f32_16x16x32_bf16 v[110:113], v[130:133], v[208:211], v[110:113]
	v_mfma_f32_16x16x32_bf16 v[106:109], v[138:141], v[208:211], v[106:109]
	v_mfma_f32_16x16x32_bf16 v[118:121], v[130:133], v[216:219], v[118:121]
	v_mfma_f32_16x16x32_bf16 v[114:117], v[138:141], v[216:219], v[114:117]
	v_mfma_f32_16x16x32_bf16 v[126:129], v[130:133], v[224:227], v[126:129]
	v_mfma_f32_16x16x32_bf16 v[122:125], v[138:141], v[224:227], v[122:125]
	v_mfma_f32_16x16x32_bf16 v[102:105], v[134:137], v[204:207], v[102:105]
	v_mfma_f32_16x16x32_bf16 v[98:101], v[142:145], v[204:207], v[98:101]
	v_mfma_f32_16x16x32_bf16 v[110:113], v[134:137], v[212:215], v[110:113]
	v_mfma_f32_16x16x32_bf16 v[106:109], v[142:145], v[212:215], v[106:109]
	v_mfma_f32_16x16x32_bf16 v[118:121], v[134:137], v[220:223], v[118:121]
	v_mfma_f32_16x16x32_bf16 v[114:117], v[142:145], v[220:223], v[114:117]
	v_mfma_f32_16x16x32_bf16 v[126:129], v[134:137], v[228:231], v[126:129]
	v_mfma_f32_16x16x32_bf16 v[122:125], v[142:145], v[228:231], v[122:125]
	s_setprio 0
	s_setprio 1
	v_mfma_f32_16x16x32_bf16 v[38:41], v[146:149], v[200:203], v[38:41]
	v_mfma_f32_16x16x32_bf16 v[34:37], v[154:157], v[200:203], v[34:37]
	v_mfma_f32_16x16x32_bf16 v[46:49], v[146:149], v[208:211], v[46:49]
	v_mfma_f32_16x16x32_bf16 v[42:45], v[154:157], v[208:211], v[42:45]
	v_mfma_f32_16x16x32_bf16 v[54:57], v[146:149], v[216:219], v[54:57]
	v_mfma_f32_16x16x32_bf16 v[50:53], v[154:157], v[216:219], v[50:53]
	v_mfma_f32_16x16x32_bf16 v[62:65], v[146:149], v[224:227], v[62:65]
	v_mfma_f32_16x16x32_bf16 v[58:61], v[154:157], v[224:227], v[58:61]
	v_mfma_f32_16x16x32_bf16 v[38:41], v[150:153], v[204:207], v[38:41]
	v_mfma_f32_16x16x32_bf16 v[34:37], v[158:161], v[204:207], v[34:37]
	v_mfma_f32_16x16x32_bf16 v[46:49], v[150:153], v[212:215], v[46:49]
	v_mfma_f32_16x16x32_bf16 v[42:45], v[158:161], v[212:215], v[42:45]
	s_setprio 3
	s_barrier
	v_mfma_f32_16x16x32_bf16 v[54:57], v[150:153], v[220:223], v[54:57]
	v_mfma_f32_16x16x32_bf16 v[50:53], v[158:161], v[220:223], v[50:53]
	v_mfma_f32_16x16x32_bf16 v[62:65], v[150:153], v[228:231], v[62:65]
	v_mfma_f32_16x16x32_bf16 v[58:61], v[158:161], v[228:231], v[58:61]
	s_setprio 0
	s_add_i32 s74, s96, s77
	v_lshl_add_u64 v[184:185], v[184:185], 0, s[38:39]
	s_mov_b32 m0, s74
	ds_read_b128 v[200:203], v199 offset:49152
	ds_read_b128 v[204:207], v199 offset:50176
	ds_read_b128 v[208:211], v199 offset:51200
	ds_read_b128 v[212:215], v199 offset:52224
	ds_read_b128 v[216:219], v199 offset:53248
	ds_read_b128 v[220:223], v199 offset:54272
	ds_read_b128 v[224:227], v199 offset:55296
	ds_read_b128 v[228:231], v199 offset:56320
	global_load_lds_dwordx4 v[184:185], off
	s_add_i32 m0, s74, 0x2000
	s_add_u32 s72, s72, 0x100080
	v_lshl_add_u64 v[184:185], v[232:233], 0, s[38:39]
	s_addc_u32 s73, s73, 0
	s_add_i32 s74, s97, s77
	global_load_lds_dwordx4 v[184:185], off
	v_lshl_add_u64 v[184:185], s[72:73], 0, v[164:165]
	s_mov_b32 m0, s74
	s_nop 0
	global_load_lds_dwordx4 v[184:185], off
	v_lshl_add_u64 v[184:185], s[72:73], 0, v[168:169]
	s_add_i32 m0, s74, 0x2000
	s_nop 0
	global_load_lds_dwordx4 v[184:185], off
	v_lshl_add_u64 v[184:185], v[234:235], 0, s[38:39]
	s_mov_b32 m0, s85
	s_nop 0
	global_load_lds_dwordx4 v[184:185], off
	v_lshl_add_u64 v[184:185], v[236:237], 0, s[38:39]
	s_mov_b32 m0, s86
	s_nop 0
	global_load_lds_dwordx4 v[184:185], off
	s_waitcnt vmcnt(8)
	s_waitcnt lgkmcnt(0)
	s_barrier
	s_setprio 1
	s_waitcnt lgkmcnt(0)
	v_mfma_f32_16x16x32_bf16 v[70:73], v[130:133], v[200:203], v[70:73]
	v_mfma_f32_16x16x32_bf16 v[66:69], v[138:141], v[200:203], v[66:69]
	v_mfma_f32_16x16x32_bf16 v[78:81], v[130:133], v[208:211], v[78:81]
	v_mfma_f32_16x16x32_bf16 v[74:77], v[138:141], v[208:211], v[74:77]
	v_mfma_f32_16x16x32_bf16 v[86:89], v[130:133], v[216:219], v[86:89]
	v_mfma_f32_16x16x32_bf16 v[82:85], v[138:141], v[216:219], v[82:85]
	v_mfma_f32_16x16x32_bf16 v[94:97], v[130:133], v[224:227], v[94:97]
	v_mfma_f32_16x16x32_bf16 v[90:93], v[138:141], v[224:227], v[90:93]
	v_mfma_f32_16x16x32_bf16 v[70:73], v[134:137], v[204:207], v[70:73]
	v_mfma_f32_16x16x32_bf16 v[66:69], v[142:145], v[204:207], v[66:69]
	v_mfma_f32_16x16x32_bf16 v[78:81], v[134:137], v[212:215], v[78:81]
	v_mfma_f32_16x16x32_bf16 v[74:77], v[142:145], v[212:215], v[74:77]
	v_mfma_f32_16x16x32_bf16 v[86:89], v[134:137], v[220:223], v[86:89]
	v_mfma_f32_16x16x32_bf16 v[82:85], v[142:145], v[220:223], v[82:85]
	v_mfma_f32_16x16x32_bf16 v[94:97], v[134:137], v[228:231], v[94:97]
	v_mfma_f32_16x16x32_bf16 v[90:93], v[142:145], v[228:231], v[90:93]
	s_setprio 0
	s_setprio 1
	v_mfma_f32_16x16x32_bf16 v[6:9], v[146:149], v[200:203], v[6:9]
	v_mfma_f32_16x16x32_bf16 v[2:5], v[154:157], v[200:203], v[2:5]
	v_mfma_f32_16x16x32_bf16 v[14:17], v[146:149], v[208:211], v[14:17]
	v_mfma_f32_16x16x32_bf16 v[10:13], v[154:157], v[208:211], v[10:13]
	v_mfma_f32_16x16x32_bf16 v[22:25], v[146:149], v[216:219], v[22:25]
	v_mfma_f32_16x16x32_bf16 v[18:21], v[154:157], v[216:219], v[18:21]
	v_mfma_f32_16x16x32_bf16 v[30:33], v[146:149], v[224:227], v[30:33]
	v_mfma_f32_16x16x32_bf16 v[26:29], v[154:157], v[224:227], v[26:29]
	v_mfma_f32_16x16x32_bf16 v[6:9], v[150:153], v[204:207], v[6:9]
	v_mfma_f32_16x16x32_bf16 v[2:5], v[158:161], v[204:207], v[2:5]
	v_mfma_f32_16x16x32_bf16 v[14:17], v[150:153], v[212:215], v[14:17]
	v_mfma_f32_16x16x32_bf16 v[10:13], v[158:161], v[212:215], v[10:13]
	s_setprio 3
	s_barrier
	v_mfma_f32_16x16x32_bf16 v[22:25], v[150:153], v[220:223], v[22:25]
	v_mfma_f32_16x16x32_bf16 v[18:21], v[158:161], v[220:223], v[18:21]
	v_mfma_f32_16x16x32_bf16 v[30:33], v[150:153], v[228:231], v[30:33]
	v_mfma_f32_16x16x32_bf16 v[26:29], v[158:161], v[228:231], v[26:29]
	s_setprio 0
	s_add_i32 s95, s95, 2
	s_add_u32 s70, s70, 0x100
	s_addc_u32 s71, s71, 0
	s_add_u32 s93, s93, 0x100
	s_addc_u32 s94, s94, 0
	s_cmp_gt_u32 s95, 61
	s_cbranch_scc0 .LBB0_743
	s_and_b64 vcc, exec, s[40:41]
	s_cbranch_vccz .LBB0_746
	s_barrier

.LBB0_902:
	ds_read_b128 v[144:147], v155
	ds_read_b128 v[148:151], v155 offset:1024
	ds_read_b128 v[158:161], v155 offset:2048
	ds_read_b128 v[162:165], v155 offset:3072
	ds_read_b128 v[166:169], v156
	ds_read_b128 v[170:173], v156 offset:1024
	ds_read_b128 v[174:177], v156 offset:2048
	ds_read_b128 v[178:181], v156 offset:3072
	s_add_u32 s50, s48, 0x100
	s_addc_u32 s51, s49, 0
	s_cmpk_eq_i32 s73, 0xa8
	s_cselect_b32 s55, s9, s51
	s_cselect_b32 s54, s8, s50
	s_cselect_b32 s53, s47, s72
	s_cselect_b32 s52, s46, s71
	v_lshl_add_u64 v[214:215], s[48:49], 0, v[136:137]
	s_add_i32 m0, s57, 0xc000
	ds_read_b128 v[182:185], v157
	ds_read_b128 v[186:189], v157 offset:1024
	ds_read_b128 v[190:193], v157 offset:2048
	ds_read_b128 v[194:197], v157 offset:3072
	ds_read_b128 v[198:201], v157 offset:4096
	ds_read_b128 v[202:205], v157 offset:5120
	ds_read_b128 v[206:209], v157 offset:6144
	ds_read_b128 v[210:213], v157 offset:7168
	global_load_lds_dwordx4 v[214:215], off
	v_lshl_add_u64 v[214:215], s[48:49], 0, v[138:139]
	s_add_i32 m0, s57, 0xe000
	s_nop 0
	global_load_lds_dwordx4 v[214:215], off
	s_waitcnt vmcnt(8)
	s_waitcnt lgkmcnt(0)
	s_barrier
	s_setprio 1
	s_waitcnt lgkmcnt(0)
	v_mfma_f32_16x16x32_bf16 v[124:127], v[144:147], v[182:185], v[124:127]
	v_mfma_f32_16x16x32_bf16 v[120:123], v[158:161], v[182:185], v[120:123]
	v_mfma_f32_16x16x32_bf16 v[116:119], v[144:147], v[190:193], v[116:119]
	v_mfma_f32_16x16x32_bf16 v[112:115], v[158:161], v[190:193], v[112:115]
	v_mfma_f32_16x16x32_bf16 v[92:95], v[144:147], v[198:201], v[92:95]
	v_mfma_f32_16x16x32_bf16 v[88:91], v[158:161], v[198:201], v[88:91]
	v_mfma_f32_16x16x32_bf16 v[76:79], v[144:147], v[206:209], v[76:79]
	v_mfma_f32_16x16x32_bf16 v[72:75], v[158:161], v[206:209], v[72:75]
	v_mfma_f32_16x16x32_bf16 v[124:127], v[148:151], v[186:189], v[124:127]
	v_mfma_f32_16x16x32_bf16 v[120:123], v[162:165], v[186:189], v[120:123]
	v_mfma_f32_16x16x32_bf16 v[116:119], v[148:151], v[194:197], v[116:119]
	v_mfma_f32_16x16x32_bf16 v[112:115], v[162:165], v[194:197], v[112:115]
	v_mfma_f32_16x16x32_bf16 v[92:95], v[148:151], v[202:205], v[92:95]
	v_mfma_f32_16x16x32_bf16 v[88:91], v[162:165], v[202:205], v[88:91]
	v_mfma_f32_16x16x32_bf16 v[76:79], v[148:151], v[210:213], v[76:79]
	v_mfma_f32_16x16x32_bf16 v[72:75], v[162:165], v[210:213], v[72:75]
	s_setprio 0
	s_setprio 1
	v_mfma_f32_16x16x32_bf16 v[108:111], v[166:169], v[182:185], v[108:111]
	v_mfma_f32_16x16x32_bf16 v[104:107], v[174:177], v[182:185], v[104:107]
	v_mfma_f32_16x16x32_bf16 v[100:103], v[166:169], v[190:193], v[100:103]
	v_mfma_f32_16x16x32_bf16 v[96:99], v[174:177], v[190:193], v[96:99]
	v_mfma_f32_16x16x32_bf16 v[84:87], v[166:169], v[198:201], v[84:87]
	v_mfma_f32_16x16x32_bf16 v[80:83], v[174:177], v[198:201], v[80:83]
	v_mfma_f32_16x16x32_bf16 v[68:71], v[166:169], v[206:209], v[68:71]
	v_mfma_f32_16x16x32_bf16 v[64:67], v[174:177], v[206:209], v[64:67]
	v_mfma_f32_16x16x32_bf16 v[108:111], v[170:173], v[186:189], v[108:111]
	v_mfma_f32_16x16x32_bf16 v[104:107], v[178:181], v[186:189], v[104:107]
	v_mfma_f32_16x16x32_bf16 v[100:103], v[170:173], v[194:197], v[100:103]
	v_mfma_f32_16x16x32_bf16 v[96:99], v[178:181], v[194:197], v[96:99]
	s_setprio 3
	s_barrier
	v_mfma_f32_16x16x32_bf16 v[84:87], v[170:173], v[202:205], v[84:87]
	v_mfma_f32_16x16x32_bf16 v[80:83], v[178:181], v[202:205], v[80:83]
	v_mfma_f32_16x16x32_bf16 v[68:71], v[170:173], v[210:213], v[68:71]
	v_mfma_f32_16x16x32_bf16 v[64:67], v[178:181], v[210:213], v[64:67]
	s_setprio 0
	s_add_i32 s48, s65, s56
	v_lshl_add_u64 v[214:215], s[52:53], 0, v[130:131]
	s_mov_b32 m0, s48
	ds_read_b128 v[182:185], v157 offset:16384
	ds_read_b128 v[186:189], v157 offset:17408
	ds_read_b128 v[190:193], v157 offset:18432
	ds_read_b128 v[194:197], v157 offset:19456
	ds_read_b128 v[198:201], v157 offset:20480
	ds_read_b128 v[202:205], v157 offset:21504
	ds_read_b128 v[206:209], v157 offset:22528
	ds_read_b128 v[210:213], v157 offset:23552
	global_load_lds_dwordx4 v[214:215], off
	s_add_i32 m0, s48, 0x2000
	s_add_u32 s48, s52, 0x2b0000
	v_lshl_add_u64 v[216:217], s[52:53], 0, v[134:135]
	s_addc_u32 s49, s53, 0
	s_add_i32 s74, s66, s56
	global_load_lds_dwordx4 v[216:217], off
	v_lshl_add_u64 v[218:219], s[48:49], 0, v[130:131]
	s_mov_b32 m0, s74
	v_lshl_add_u64 v[220:221], s[54:55], 0, v[132:133]
	global_load_lds_dwordx4 v[218:219], off
	v_lshl_add_u64 v[218:219], s[48:49], 0, v[134:135]
	s_add_i32 m0, s74, 0x2000
	s_nop 0
	global_load_lds_dwordx4 v[218:219], off
	v_lshl_add_u64 v[218:219], s[54:55], 0, v[128:129]
	s_mov_b32 m0, s57
	s_nop 0
	global_load_lds_dwordx4 v[218:219], off
	s_mov_b32 m0, s58
	s_nop 0
	global_load_lds_dwordx4 v[220:221], off
	s_waitcnt vmcnt(8)
	s_waitcnt lgkmcnt(0)
	s_barrier
	s_setprio 1
	s_waitcnt lgkmcnt(0)
	v_mfma_f32_16x16x32_bf16 v[60:63], v[144:147], v[182:185], v[60:63]
	v_mfma_f32_16x16x32_bf16 v[56:59], v[158:161], v[182:185], v[56:59]
	v_mfma_f32_16x16x32_bf16 v[44:47], v[144:147], v[190:193], v[44:47]
	v_mfma_f32_16x16x32_bf16 v[40:43], v[158:161], v[190:193], v[40:43]
	v_mfma_f32_16x16x32_bf16 v[28:31], v[144:147], v[198:201], v[28:31]
	v_mfma_f32_16x16x32_bf16 v[24:27], v[158:161], v[198:201], v[24:27]
	v_mfma_f32_16x16x32_bf16 v[12:15], v[144:147], v[206:209], v[12:15]
	v_mfma_f32_16x16x32_bf16 v[8:11], v[158:161], v[206:209], v[8:11]
	v_mfma_f32_16x16x32_bf16 v[60:63], v[148:151], v[186:189], v[60:63]
	v_mfma_f32_16x16x32_bf16 v[56:59], v[162:165], v[186:189], v[56:59]
	v_mfma_f32_16x16x32_bf16 v[44:47], v[148:151], v[194:197], v[44:47]
	v_mfma_f32_16x16x32_bf16 v[40:43], v[162:165], v[194:197], v[40:43]
	v_mfma_f32_16x16x32_bf16 v[28:31], v[148:151], v[202:205], v[28:31]
	v_mfma_f32_16x16x32_bf16 v[24:27], v[162:165], v[202:205], v[24:27]
	v_mfma_f32_16x16x32_bf16 v[12:15], v[148:151], v[210:213], v[12:15]
	v_mfma_f32_16x16x32_bf16 v[8:11], v[162:165], v[210:213], v[8:11]
	s_setprio 0
	s_setprio 1
	v_mfma_f32_16x16x32_bf16 v[52:55], v[166:169], v[182:185], v[52:55]
	v_mfma_f32_16x16x32_bf16 v[48:51], v[174:177], v[182:185], v[48:51]
	v_mfma_f32_16x16x32_bf16 v[36:39], v[166:169], v[190:193], v[36:39]
	v_mfma_f32_16x16x32_bf16 v[32:35], v[174:177], v[190:193], v[32:35]
	v_mfma_f32_16x16x32_bf16 v[20:23], v[166:169], v[198:201], v[20:23]
	v_mfma_f32_16x16x32_bf16 v[16:19], v[174:177], v[198:201], v[16:19]
	v_mfma_f32_16x16x32_bf16 v[4:7], v[166:169], v[206:209], v[4:7]
	v_mfma_f32_16x16x32_bf16 v[0:3], v[174:177], v[206:209], v[0:3]
	v_mfma_f32_16x16x32_bf16 v[52:55], v[170:173], v[186:189], v[52:55]
	v_mfma_f32_16x16x32_bf16 v[48:51], v[178:181], v[186:189], v[48:51]
	v_mfma_f32_16x16x32_bf16 v[36:39], v[170:173], v[194:197], v[36:39]
	v_mfma_f32_16x16x32_bf16 v[32:35], v[178:181], v[194:197], v[32:35]
	s_setprio 3
	s_barrier
	v_mfma_f32_16x16x32_bf16 v[20:23], v[170:173], v[202:205], v[20:23]
	v_mfma_f32_16x16x32_bf16 v[16:19], v[178:181], v[202:205], v[16:19]
	v_mfma_f32_16x16x32_bf16 v[4:7], v[170:173], v[210:213], v[4:7]
	v_mfma_f32_16x16x32_bf16 v[0:3], v[178:181], v[210:213], v[0:3]
	s_setprio 0
	s_add_i32 s74, 0, 0x18000
	s_add_i32 s75, 0, 0x1c000
	v_add_u32_e32 v162, s74, v153
	v_add_u32_e32 v178, s75, v153
	ds_read_b128 v[144:147], v162
	ds_read_b128 v[148:151], v162 offset:1024
	ds_read_b128 v[158:161], v162 offset:2048
	ds_read_b128 v[162:165], v162 offset:3072
	ds_read_b128 v[166:169], v178
	ds_read_b128 v[170:173], v178 offset:1024
	ds_read_b128 v[174:177], v178 offset:2048
	ds_read_b128 v[178:181], v178 offset:3072
	s_add_u32 s48, s54, 0x2b0000
	s_addc_u32 s49, s55, 0
	s_mov_b32 m0, s59
	v_lshl_add_u64 v[222:223], s[48:49], 0, v[128:129]
	ds_read_b128 v[182:185], v157 offset:32768
	ds_read_b128 v[186:189], v157 offset:33792
	ds_read_b128 v[190:193], v157 offset:34816
	ds_read_b128 v[194:197], v157 offset:35840
	ds_read_b128 v[198:201], v157 offset:36864
	ds_read_b128 v[202:205], v157 offset:37888
	ds_read_b128 v[206:209], v157 offset:38912
	ds_read_b128 v[210:213], v157 offset:39936
	global_load_lds_dwordx4 v[222:223], off
	v_lshl_add_u64 v[222:223], s[48:49], 0, v[132:133]
	s_mov_b32 m0, s60
	s_nop 0
	global_load_lds_dwordx4 v[222:223], off
	s_waitcnt vmcnt(8)
	s_waitcnt lgkmcnt(0)
	s_barrier
	s_setprio 1
	s_waitcnt lgkmcnt(0)
	v_mfma_f32_16x16x32_bf16 v[124:127], v[144:147], v[182:185], v[124:127]
	v_mfma_f32_16x16x32_bf16 v[120:123], v[158:161], v[182:185], v[120:123]
	v_mfma_f32_16x16x32_bf16 v[116:119], v[144:147], v[190:193], v[116:119]
	v_mfma_f32_16x16x32_bf16 v[112:115], v[158:161], v[190:193], v[112:115]
	v_mfma_f32_16x16x32_bf16 v[92:95], v[144:147], v[198:201], v[92:95]
	v_mfma_f32_16x16x32_bf16 v[88:91], v[158:161], v[198:201], v[88:91]
	v_mfma_f32_16x16x32_bf16 v[76:79], v[144:147], v[206:209], v[76:79]
	v_mfma_f32_16x16x32_bf16 v[72:75], v[158:161], v[206:209], v[72:75]
	v_mfma_f32_16x16x32_bf16 v[124:127], v[148:151], v[186:189], v[124:127]
	v_mfma_f32_16x16x32_bf16 v[120:123], v[162:165], v[186:189], v[120:123]
	v_mfma_f32_16x16x32_bf16 v[116:119], v[148:151], v[194:197], v[116:119]
	v_mfma_f32_16x16x32_bf16 v[112:115], v[162:165], v[194:197], v[112:115]
	v_mfma_f32_16x16x32_bf16 v[92:95], v[148:151], v[202:205], v[92:95]
	v_mfma_f32_16x16x32_bf16 v[88:91], v[162:165], v[202:205], v[88:91]
	v_mfma_f32_16x16x32_bf16 v[76:79], v[148:151], v[210:213], v[76:79]
	v_mfma_f32_16x16x32_bf16 v[72:75], v[162:165], v[210:213], v[72:75]
	s_setprio 0
	s_setprio 1
	v_mfma_f32_16x16x32_bf16 v[108:111], v[166:169], v[182:185], v[108:111]
	v_mfma_f32_16x16x32_bf16 v[104:107], v[174:177], v[182:185], v[104:107]
	v_mfma_f32_16x16x32_bf16 v[100:103], v[166:169], v[190:193], v[100:103]
	v_mfma_f32_16x16x32_bf16 v[96:99], v[174:177], v[190:193], v[96:99]
	v_mfma_f32_16x16x32_bf16 v[84:87], v[166:169], v[198:201], v[84:87]
	v_mfma_f32_16x16x32_bf16 v[80:83], v[174:177], v[198:201], v[80:83]
	v_mfma_f32_16x16x32_bf16 v[68:71], v[166:169], v[206:209], v[68:71]
	v_mfma_f32_16x16x32_bf16 v[64:67], v[174:177], v[206:209], v[64:67]
	v_mfma_f32_16x16x32_bf16 v[108:111], v[170:173], v[186:189], v[108:111]
	v_mfma_f32_16x16x32_bf16 v[104:107], v[178:181], v[186:189], v[104:107]
	v_mfma_f32_16x16x32_bf16 v[100:103], v[170:173], v[194:197], v[100:103]
	v_mfma_f32_16x16x32_bf16 v[96:99], v[178:181], v[194:197], v[96:99]
	s_setprio 3
	s_barrier
	v_mfma_f32_16x16x32_bf16 v[84:87], v[170:173], v[202:205], v[84:87]
	v_mfma_f32_16x16x32_bf16 v[80:83], v[178:181], v[202:205], v[80:83]
	v_mfma_f32_16x16x32_bf16 v[68:71], v[170:173], v[210:213], v[68:71]
	v_mfma_f32_16x16x32_bf16 v[64:67], v[178:181], v[210:213], v[64:67]
	s_setprio 0
	s_add_i32 s48, s74, s56
	v_lshl_add_u64 v[214:215], v[214:215], 0, s[30:31]
	s_mov_b32 m0, s48
	ds_read_b128 v[182:185], v157 offset:49152
	ds_read_b128 v[186:189], v157 offset:50176
	ds_read_b128 v[190:193], v157 offset:51200
	ds_read_b128 v[194:197], v157 offset:52224
	ds_read_b128 v[198:201], v157 offset:53248
	ds_read_b128 v[202:205], v157 offset:54272
	ds_read_b128 v[206:209], v157 offset:55296
	ds_read_b128 v[210:213], v157 offset:56320
	global_load_lds_dwordx4 v[214:215], off
	s_add_i32 m0, s48, 0x2000
	s_add_u32 s48, s52, 0x2b0080
	v_lshl_add_u64 v[214:215], v[216:217], 0, s[30:31]
	s_addc_u32 s49, s53, 0
	s_add_i32 s52, s75, s56
	global_load_lds_dwordx4 v[214:215], off
	v_lshl_add_u64 v[214:215], s[48:49], 0, v[130:131]
	s_mov_b32 m0, s52
	s_nop 0
	global_load_lds_dwordx4 v[214:215], off
	v_lshl_add_u64 v[214:215], s[48:49], 0, v[134:135]
	s_add_i32 m0, s52, 0x2000
	s_nop 0
	global_load_lds_dwordx4 v[214:215], off
	v_lshl_add_u64 v[214:215], v[218:219], 0, s[30:31]
	s_mov_b32 m0, s62
	s_nop 0
	global_load_lds_dwordx4 v[214:215], off
	v_lshl_add_u64 v[214:215], v[220:221], 0, s[30:31]
	s_mov_b32 m0, s63
	s_nop 0
	global_load_lds_dwordx4 v[214:215], off
	s_waitcnt vmcnt(8)
	s_waitcnt lgkmcnt(0)
	s_barrier
	s_setprio 1
	s_waitcnt lgkmcnt(0)
	v_mfma_f32_16x16x32_bf16 v[60:63], v[144:147], v[182:185], v[60:63]
	v_mfma_f32_16x16x32_bf16 v[56:59], v[158:161], v[182:185], v[56:59]
	v_mfma_f32_16x16x32_bf16 v[44:47], v[144:147], v[190:193], v[44:47]
	v_mfma_f32_16x16x32_bf16 v[40:43], v[158:161], v[190:193], v[40:43]
	v_mfma_f32_16x16x32_bf16 v[28:31], v[144:147], v[198:201], v[28:31]
	v_mfma_f32_16x16x32_bf16 v[24:27], v[158:161], v[198:201], v[24:27]
	v_mfma_f32_16x16x32_bf16 v[12:15], v[144:147], v[206:209], v[12:15]
	v_mfma_f32_16x16x32_bf16 v[8:11], v[158:161], v[206:209], v[8:11]
	v_mfma_f32_16x16x32_bf16 v[60:63], v[148:151], v[186:189], v[60:63]
	v_mfma_f32_16x16x32_bf16 v[56:59], v[162:165], v[186:189], v[56:59]
	v_mfma_f32_16x16x32_bf16 v[44:47], v[148:151], v[194:197], v[44:47]
	v_mfma_f32_16x16x32_bf16 v[40:43], v[162:165], v[194:197], v[40:43]
	v_mfma_f32_16x16x32_bf16 v[28:31], v[148:151], v[202:205], v[28:31]
	v_mfma_f32_16x16x32_bf16 v[24:27], v[162:165], v[202:205], v[24:27]
	v_mfma_f32_16x16x32_bf16 v[12:15], v[148:151], v[210:213], v[12:15]
	v_mfma_f32_16x16x32_bf16 v[8:11], v[162:165], v[210:213], v[8:11]
	s_setprio 0
	s_setprio 1
	v_mfma_f32_16x16x32_bf16 v[52:55], v[166:169], v[182:185], v[52:55]
	v_mfma_f32_16x16x32_bf16 v[48:51], v[174:177], v[182:185], v[48:51]
	v_mfma_f32_16x16x32_bf16 v[36:39], v[166:169], v[190:193], v[36:39]
	v_mfma_f32_16x16x32_bf16 v[32:35], v[174:177], v[190:193], v[32:35]
	v_mfma_f32_16x16x32_bf16 v[20:23], v[166:169], v[198:201], v[20:23]
	v_mfma_f32_16x16x32_bf16 v[16:19], v[174:177], v[198:201], v[16:19]
	v_mfma_f32_16x16x32_bf16 v[4:7], v[166:169], v[206:209], v[4:7]
	v_mfma_f32_16x16x32_bf16 v[0:3], v[174:177], v[206:209], v[0:3]
	v_mfma_f32_16x16x32_bf16 v[52:55], v[170:173], v[186:189], v[52:55]
	v_mfma_f32_16x16x32_bf16 v[48:51], v[178:181], v[186:189], v[48:51]
	v_mfma_f32_16x16x32_bf16 v[36:39], v[170:173], v[194:197], v[36:39]
	v_mfma_f32_16x16x32_bf16 v[32:35], v[178:181], v[194:197], v[32:35]
	s_setprio 3
	s_barrier
	v_mfma_f32_16x16x32_bf16 v[20:23], v[170:173], v[202:205], v[20:23]
	v_mfma_f32_16x16x32_bf16 v[16:19], v[178:181], v[202:205], v[16:19]
	v_mfma_f32_16x16x32_bf16 v[4:7], v[170:173], v[210:213], v[4:7]
	v_mfma_f32_16x16x32_bf16 v[0:3], v[178:181], v[210:213], v[0:3]
	s_setprio 0
	s_add_i32 s73, s73, 2
	s_add_u32 s71, s71, 0x100
	s_addc_u32 s72, s72, 0
	s_cmpk_gt_u32 s73, 0xa9
	s_mov_b64 s[48:49], s[50:51]
	s_cbranch_scc0 .LBB0_902
	s_and_b64 vcc, exec, s[34:35]
	s_cbranch_vccz .LBB0_905
	s_barrier
